# v016 + G2 epilogue: x tile preloaded into accumulators at tile start (no x loads in epilogue); mix: first gu-load wait moved after the MFMA section
# baseline (speedup 1.0000x reference)
; #define LAS __attribute__((address_space(3)))
; __device__ __forceinline__ void mix_phase(const Params& p, LAS unsigned char* lds, int G, bool dry) {
;     ...
;         u32x2 ur[4][4]; float bias[4];
;         bf16_t* const gup = gu + (size_t)(row_base + 64 * wr + fr) * GW + g * 256 + 64 * wc + 4 * fq;
; #pragma unroll
;         for (int m = 0; m < 4; ++m) {
;             const int tt = 64 * wr + 16 * m + fr; bias[m] = p.bsp[g * 128 + (smp ? (tt & 31) : tt)];
; #pragma unroll
;             for (int n = 0; n < 4; ++n) ur[m][n] = __builtin_nontemporal_load((const u32x2*)(gup + (size_t)m * 16 * GW + 16 * n));
;         }
;         __syncthreads();
;         f32x4 acc[4][4];
; #pragma unroll
;         for (int m = 0; m < 4; ++m)
; #pragma unroll
;             for (int n = 0; n < 4; ++n) acc[m][n] = (f32x4){0.f, 0.f, 0.f, 0.f};
; #pragma unroll
;         for (int ks = 0; ks < 4; ++ks) {
;             bf16x8 af[4], bfr[4];
; #pragma unroll
;             for (int m = 0; m < 4; ++m) af[m] = *(const LAS bf16x8*)(Wl + (64 * wr + 16 * m + fr) * MIX_WP + 32 * ks + 8 * fq);
; #pragma unroll
;             for (int n = 0; n < 4; ++n) {
;                 const LAS bf16_t* a0 = Vl + (32 * ks + 8 * fq + (fr >> 2)) * MIX_VP + 64 * wc + 16 * n + 4 * (fr & 3);
;                 const s16x4 lo = __builtin_amdgcn_ds_read_tr16_b64_v4i16((LAS s16x4*)a0), hi = __builtin_amdgcn_ds_read_tr16_b64_v4i16((LAS s16x4*)(a0 + 4 * MIX_VP));
;                 bfr[n] = (bf16x8){lo[0], lo[1], lo[2], lo[3], hi[0], hi[1], hi[2], hi[3]};
;             }
; #pragma unroll
;             for (int m = 0; m < 4; ++m)
; #pragma unroll
;                 for (int n = 0; n < 4; ++n) acc[m][n] = __builtin_amdgcn_mfma_f32_16x16x32_bf16(bfr[n], af[m], acc[m][n], 0, 0, 0);
;         }
.LBB0_214:
	v_cvt_pk_bf16_f32 v0, v0, v1
	v_cvt_pk_bf16_f32 v1, v2, v3
	v_cvt_pk_bf16_f32 v2, v4, v5
	v_cvt_pk_bf16_f32 v3, v6, v7
	ds_write_b128 v127, v[0:3] offset:34816
	v_add_u32_e32 v0, s37, v95
	v_ashrrev_i32_e32 v1, 31, v0
	v_lshlrev_b64 v[0:1], 13, v[0:1]
	v_lshl_add_u64 v[0:1], s[0:1], 0, v[0:1]
	s_lshl_b32 s18, s34, 1
	v_lshl_add_u64 v[0:1], v[0:1], 0, s[18:19]
	v_lshl_add_u64 v[0:1], v[0:1], 0, v[82:83]
	v_mov_b32_e32 v93, v83
	s_lshl_b32 s10, s36, 7
	v_lshl_add_u64 v[34:35], v[0:1], 0, v[92:93]
	v_add_u32_e32 v0, s10, v11
	v_ashrrev_i32_e32 v1, 31, v0
	v_add_u32_e32 v2, s10, v10
	v_lshl_add_u64 v[0:1], v[0:1], 2, s[76:77]
	v_ashrrev_i32_e32 v3, 31, v2
	global_load_dwordx2 v[46:47], v[34:35], off nt
	global_load_dwordx2 v[44:45], v[34:35], off offset:32 nt
	global_load_dwordx2 v[42:43], v[34:35], off offset:64 nt
	global_load_dwordx2 v[38:39], v[34:35], off offset:96 nt
	v_lshl_add_u64 v[2:3], v[2:3], 2, s[76:77]
	global_load_dword v40, v[0:1], off
	global_load_dword v28, v[2:3], off
	v_add_co_u32_e32 v22, vcc, s40, v34
	v_add_u32_e32 v0, s10, v9
	s_nop 0
	v_addc_co_u32_e32 v23, vcc, 0, v35, vcc
	global_load_dwordx2 v[36:37], v[22:23], off nt
	global_load_dwordx2 v[32:33], v[22:23], off offset:32 nt
	global_load_dwordx2 v[30:31], v[22:23], off offset:64 nt
	global_load_dwordx2 v[26:27], v[22:23], off offset:96 nt
	v_ashrrev_i32_e32 v1, 31, v0
	v_lshl_add_u64 v[0:1], v[0:1], 2, s[76:77]
	global_load_dword v16, v[0:1], off
	v_add_co_u32_e32 v10, vcc, s41, v34
	v_add_u32_e32 v0, s10, v8
	s_nop 0
	v_addc_co_u32_e32 v11, vcc, 0, v35, vcc
	global_load_dwordx2 v[24:25], v[10:11], off nt
	global_load_dwordx2 v[20:21], v[10:11], off offset:32 nt
	global_load_dwordx2 v[18:19], v[10:11], off offset:64 nt
	global_load_dwordx2 v[14:15], v[10:11], off offset:96 nt
	v_ashrrev_i32_e32 v1, 31, v0
	v_lshl_add_u64 v[0:1], v[0:1], 2, s[76:77]
	global_load_dword v4, v[0:1], off
	v_add_co_u32_e32 v0, vcc, s42, v34
	v_addc_co_u32_e32 v1, vcc, 0, v35, vcc
	global_load_dwordx2 v[12:13], v[0:1], off nt
	global_load_dwordx2 v[8:9], v[0:1], off offset:32 nt
	global_load_dwordx2 v[6:7], v[0:1], off offset:64 nt
	global_load_dwordx2 v[2:3], v[0:1], off offset:96 nt
	s_waitcnt lgkmcnt(0)
	s_barrier
	ds_read_b64_tr_b16 v[50:51], v116 offset:36928
	ds_read_b64_tr_b16 v[48:49], v116 offset:34816
	ds_read_b128 v[52:55], v128
	ds_read_b64_tr_b16 v[58:59], v116 offset:36960
	ds_read_b64_tr_b16 v[56:57], v116 offset:34848
	ds_read_b64_tr_b16 v[60:61], v116 offset:34880
	ds_read_b64_tr_b16 v[64:65], v116 offset:34912
	ds_read_b64_tr_b16 v[62:63], v116 offset:36992
	ds_read_b64_tr_b16 v[66:67], v116 offset:37024
	ds_read_b128 v[68:71], v128 offset:64
	ds_read_b128 v[136:139], v128 offset:4352
	ds_read_b128 v[140:143], v128 offset:4416
	ds_read_b128 v[156:159], v128 offset:8704
	ds_read_b128 v[160:163], v128 offset:8768
	ds_read_b128 v[176:179], v128 offset:13056
	ds_read_b128 v[180:183], v128 offset:13120
	s_waitcnt lgkmcnt(13)
	v_mfma_f32_16x16x32_bf16 v[72:75], v[48:51], v[52:55], 0
	ds_read_b64_tr_b16 v[184:185], v116 offset:51712
	ds_read_b64_tr_b16 v[186:187], v116 offset:53824
	s_waitcnt lgkmcnt(13)
	v_mfma_f32_16x16x32_bf16 v[76:79], v[56:59], v[52:55], 0
	s_waitcnt lgkmcnt(10)
	v_mfma_f32_16x16x32_bf16 v[132:135], v[60:63], v[52:55], 0
	s_waitcnt lgkmcnt(9)
	v_mfma_f32_16x16x32_bf16 v[52:55], v[64:67], v[52:55], 0
	s_waitcnt lgkmcnt(7)
	v_mfma_f32_16x16x32_bf16 v[144:147], v[48:51], v[136:139], 0
	v_mfma_f32_16x16x32_bf16 v[148:151], v[56:59], v[136:139], 0
	v_mfma_f32_16x16x32_bf16 v[152:155], v[60:63], v[136:139], 0
	v_mfma_f32_16x16x32_bf16 v[136:139], v[64:67], v[136:139], 0
	s_waitcnt lgkmcnt(5)
	v_mfma_f32_16x16x32_bf16 v[164:167], v[48:51], v[156:159], 0
	v_mfma_f32_16x16x32_bf16 v[168:171], v[56:59], v[156:159], 0
	v_mfma_f32_16x16x32_bf16 v[172:175], v[60:63], v[156:159], 0
	v_mfma_f32_16x16x32_bf16 v[156:159], v[64:67], v[156:159], 0
	s_waitcnt lgkmcnt(3)
	v_mfma_f32_16x16x32_bf16 v[48:51], v[48:51], v[176:179], 0
	v_mfma_f32_16x16x32_bf16 v[56:59], v[56:59], v[176:179], 0
	v_mfma_f32_16x16x32_bf16 v[60:63], v[60:63], v[176:179], 0
	v_mfma_f32_16x16x32_bf16 v[64:67], v[64:67], v[176:179], 0
	ds_read_b64_tr_b16 v[178:179], v116 offset:53856
	ds_read_b64_tr_b16 v[176:177], v116 offset:51744
	ds_read_b64_tr_b16 v[188:189], v116 offset:51776
	ds_read_b64_tr_b16 v[196:197], v116 offset:51808
	ds_read_b64_tr_b16 v[190:191], v116 offset:53888
	ds_read_b64_tr_b16 v[198:199], v116 offset:53920
	s_waitcnt lgkmcnt(6)
	v_mfma_f32_16x16x32_bf16 v[72:75], v[184:187], v[68:71], v[72:75]
	s_waitcnt lgkmcnt(4)
	v_mfma_f32_16x16x32_bf16 v[76:79], v[176:179], v[68:71], v[76:79]
	s_waitcnt lgkmcnt(1)
	v_mfma_f32_16x16x32_bf16 v[132:135], v[188:191], v[68:71], v[132:135]
	s_waitcnt lgkmcnt(0)
; #define LAS __attribute__((address_space(3)))
; __device__ __forceinline__ unsigned cvt_pk_bf16(float lo, float hi) { unsigned r; asm volatile("v_cvt_pk_bf16_f32 %0, %1, %2" : "=v"(r) : "v"(lo), "v"(hi)); return r; }
; __device__ __forceinline__ float bf_lo(unsigned w) { return __uint_as_float(w << 16); }
; __device__ __forceinline__ float bf_hi(unsigned w) { return __uint_as_float(w & 0xffff0000u); }
; __device__ __forceinline__ void mix_phase(const Params& p, LAS unsigned char* lds, int G, bool dry) {
;     ...
;         for (int ks = 0; ks < 4; ++ks) {
;             bf16x8 af[4], bfr[4];
; #pragma unroll
;             for (int m = 0; m < 4; ++m) af[m] = *(const LAS bf16x8*)(Wl + (64 * wr + 16 * m + fr) * MIX_WP + 32 * ks + 8 * fq);
; #pragma unroll
;             for (int n = 0; n < 4; ++n) {
;                 const LAS bf16_t* a0 = Vl + (32 * ks + 8 * fq + (fr >> 2)) * MIX_VP + 64 * wc + 16 * n + 4 * (fr & 3);
;                 const s16x4 lo = __builtin_amdgcn_ds_read_tr16_b64_v4i16((LAS s16x4*)a0), hi = __builtin_amdgcn_ds_read_tr16_b64_v4i16((LAS s16x4*)(a0 + 4 * MIX_VP));
;                 bfr[n] = (bf16x8){lo[0], lo[1], lo[2], lo[3], hi[0], hi[1], hi[2], hi[3]};
;             }
; #pragma unroll
;             for (int m = 0; m < 4; ++m)
; #pragma unroll
;                 for (int n = 0; n < 4; ++n) acc[m][n] = __builtin_amdgcn_mfma_f32_16x16x32_bf16(bfr[n], af[m], acc[m][n], 0, 0, 0);
;         }
; #pragma unroll
;         for (int m = 0; m < 4; ++m) {
; #pragma unroll
;             for (int n = 0; n < 4; ++n) {
;                 const f32x4 a = acc[m][n] + bias[m]; const u32x2 u2 = ur[m][n];
;                 u32x2 w; w.x = cvt_pk_bf16(bf_lo(u2.x) * a[0], bf_hi(u2.x) * a[1]); w.y = cvt_pk_bf16(bf_lo(u2.y) * a[2], bf_hi(u2.y) * a[3]);
;                 if (!dry) *(u32x2*)(gup + (size_t)m * 16 * GW + 16 * n) = w;
;             }
;         }
	v_mfma_f32_16x16x32_bf16 v[52:55], v[196:199], v[68:71], v[52:55]
	v_mfma_f32_16x16x32_bf16 v[68:71], v[184:187], v[140:143], v[144:147]
	v_mfma_f32_16x16x32_bf16 v[144:147], v[176:179], v[140:143], v[148:151]
	v_mfma_f32_16x16x32_bf16 v[148:151], v[188:191], v[140:143], v[152:155]
	v_mfma_f32_16x16x32_bf16 v[136:139], v[196:199], v[140:143], v[136:139]
	v_mfma_f32_16x16x32_bf16 v[140:143], v[184:187], v[160:163], v[164:167]
	v_mfma_f32_16x16x32_bf16 v[152:155], v[176:179], v[160:163], v[168:171]
	v_mfma_f32_16x16x32_bf16 v[164:167], v[188:191], v[160:163], v[172:175]
	v_mfma_f32_16x16x32_bf16 v[156:159], v[196:199], v[160:163], v[156:159]
	ds_read_b128 v[160:163], v128 offset:128
	ds_read_b64_tr_b16 v[170:171], v117 offset:35904
	v_mfma_f32_16x16x32_bf16 v[48:51], v[184:187], v[180:183], v[48:51]
	v_mfma_f32_16x16x32_bf16 v[56:59], v[176:179], v[180:183], v[56:59]
	ds_read_b64_tr_b16 v[168:169], v117 offset:33792
	ds_read_b64_tr_b16 v[172:173], v117 offset:33824
	ds_read_b64_tr_b16 v[176:177], v117 offset:33856
	ds_read_b64_tr_b16 v[184:185], v117 offset:33888
	v_mfma_f32_16x16x32_bf16 v[60:63], v[188:191], v[180:183], v[60:63]
	v_mfma_f32_16x16x32_bf16 v[64:67], v[196:199], v[180:183], v[64:67]
	ds_read_b64_tr_b16 v[174:175], v117 offset:35936
	ds_read_b64_tr_b16 v[178:179], v117 offset:35968
	ds_read_b64_tr_b16 v[186:187], v117 offset:36000
	ds_read_b128 v[180:183], v128 offset:192
	ds_read_b128 v[188:191], v128 offset:4480
	ds_read_b128 v[196:199], v128 offset:4544
	ds_read_b128 v[200:203], v128 offset:8832
	ds_read_b128 v[204:207], v128 offset:8896
	ds_read_b128 v[208:211], v128 offset:13184
	ds_read_b128 v[212:215], v128 offset:13248
	ds_read_b64_tr_b16 v[216:217], v117 offset:50688
	ds_read_b64_tr_b16 v[218:219], v117 offset:52800
	s_waitcnt lgkmcnt(14)
	v_mfma_f32_16x16x32_bf16 v[72:75], v[168:171], v[160:163], v[72:75]
	ds_read_b64_tr_b16 v[220:221], v117 offset:50720
	ds_read_b64_tr_b16 v[224:225], v117 offset:50752
	ds_read_b64_tr_b16 v[228:229], v117 offset:50784
	ds_read_b64_tr_b16 v[222:223], v117 offset:52832
	ds_read_b64_tr_b16 v[226:227], v117 offset:52864
	ds_read_b64_tr_b16 v[230:231], v117 offset:52896
	s_waitcnt lgkmcnt(14)
	v_mfma_f32_16x16x32_bf16 v[76:79], v[172:175], v[160:163], v[76:79]
	s_waitcnt lgkmcnt(6)
	v_mfma_f32_16x16x32_bf16 v[72:75], v[216:219], v[180:183], v[72:75]
	s_waitcnt lgkmcnt(2)
	v_mfma_f32_16x16x32_bf16 v[76:79], v[220:223], v[180:183], v[76:79]
	v_mfma_f32_16x16x32_bf16 v[132:135], v[176:179], v[160:163], v[132:135]
	s_waitcnt vmcnt(15)
	v_lshlrev_b32_e32 v5, 16, v46
	v_and_b32_e32 v17, 0xffff0000, v46
	s_nop 3
	v_pk_add_f32 v[72:73], v[40:41], v[72:73] op_sel_hi:[0,1]
	v_mul_f32_e32 v5, v72, v5
	v_mul_f32_e32 v17, v73, v17
	v_mfma_f32_16x16x32_bf16 v[52:55], v[184:187], v[160:163], v[52:55]
	v_add_f32_e64 v160, v40, v74
	v_add_f32_e64 v161, v40, v75
	v_cvt_pk_bf16_f32 v46, v5, v17
	v_lshlrev_b32_e32 v5, 16, v47
	v_and_b32_e32 v17, 0xffff0000, v47
	v_mul_f32_e32 v5, v160, v5
	v_mul_f32_e32 v17, v161, v17
	v_mfma_f32_16x16x32_bf16 v[72:75], v[172:175], v[188:191], v[144:147]
	v_cvt_pk_bf16_f32 v47, v5, v17
	v_lshlrev_b32_e32 v5, 16, v44
	v_and_b32_e32 v17, 0xffff0000, v44
	v_mfma_f32_16x16x32_bf16 v[144:147], v[176:179], v[188:191], v[148:151]
	global_store_dwordx2 v[34:35], v[46:47], off
	v_pk_add_f32 v[46:47], v[40:41], v[78:79] op_sel_hi:[0,1]
	s_nop 0
	v_pk_add_f32 v[148:149], v[40:41], v[76:77] op_sel_hi:[0,1]
	v_mul_f32_e32 v5, v148, v5
	v_mul_f32_e32 v17, v149, v17
	v_cvt_pk_bf16_f32 v148, v5, v17
	v_lshlrev_b32_e32 v5, 16, v45
	v_and_b32_e32 v17, 0xffff0000, v45
	v_mul_f32_e32 v5, v46, v5
	v_mul_f32_e32 v17, v47, v17
	s_waitcnt lgkmcnt(1)
	v_mfma_f32_16x16x32_bf16 v[44:47], v[224:227], v[180:183], v[132:135]
	v_cvt_pk_bf16_f32 v149, v5, v17
	v_lshlrev_b32_e32 v5, 16, v42
	v_and_b32_e32 v17, 0xffff0000, v42
	v_mfma_f32_16x16x32_bf16 v[68:71], v[168:171], v[188:191], v[68:71]
	global_store_dwordx2 v[34:35], v[148:149], off offset:32
	s_nop 3
	v_pk_add_f32 v[150:151], v[40:41], v[44:45] op_sel_hi:[0,1]
	v_mul_f32_e32 v5, v150, v5
	s_waitcnt lgkmcnt(0)
	v_mfma_f32_16x16x32_bf16 v[52:55], v[228:231], v[180:183], v[52:55]
	v_mul_f32_e32 v17, v151, v17
	v_pk_add_f32 v[148:149], v[40:41], v[46:47] op_sel_hi:[0,1]
	v_cvt_pk_bf16_f32 v42, v5, v17
	v_lshlrev_b32_e32 v5, 16, v43
	v_and_b32_e32 v17, 0xffff0000, v43
	v_mul_f32_e32 v5, v148, v5
	v_mul_f32_e32 v17, v149, v17
	v_cvt_pk_bf16_f32 v43, v5, v17
	global_store_dwordx2 v[34:35], v[42:43], off offset:64
	s_nop 0
	v_pk_add_f32 v[148:149], v[40:41], v[54:55] op_sel_hi:[0,1]
	v_pk_add_f32 v[52:53], v[40:41], v[52:53] op_sel_hi:[0,1]
	v_lshlrev_b32_e32 v5, 16, v38
	v_mfma_f32_16x16x32_bf16 v[40:43], v[176:179], v[208:211], v[60:63]
	v_and_b32_e32 v17, 0xffff0000, v38
	v_mul_f32_e32 v5, v52, v5
	v_mul_f32_e32 v17, v53, v17
	v_mfma_f32_16x16x32_bf16 v[60:63], v[216:219], v[196:199], v[68:71]
	v_cvt_pk_bf16_f32 v38, v5, v17
	v_lshlrev_b32_e32 v5, 16, v39
	v_and_b32_e32 v17, 0xffff0000, v39
	v_mul_f32_e32 v5, v148, v5
	v_mul_f32_e32 v17, v149, v17
	v_cvt_pk_bf16_f32 v39, v5, v17
	v_mfma_f32_16x16x32_bf16 v[52:55], v[184:187], v[208:211], v[64:67]
	global_store_dwordx2 v[34:35], v[38:39], off offset:96
	s_waitcnt vmcnt(18)
	s_nop 0
	v_pk_add_f32 v[38:39], v[28:29], v[60:61] op_sel_hi:[0,1]
	s_waitcnt vmcnt(17)
	v_lshlrev_b32_e32 v5, 16, v36
	v_mfma_f32_16x16x32_bf16 v[64:67], v[220:223], v[196:199], v[72:75]
	v_and_b32_e32 v17, 0xffff0000, v36
	v_mul_f32_e32 v5, v38, v5
	v_mul_f32_e32 v17, v39, v17
	v_pk_add_f32 v[34:35], v[28:29], v[62:63] op_sel_hi:[0,1]
	v_cvt_pk_bf16_f32 v38, v5, v17
	v_lshlrev_b32_e32 v5, 16, v37
	v_and_b32_e32 v17, 0xffff0000, v37
	v_mul_f32_e32 v5, v34, v5
	v_mul_f32_e32 v17, v35, v17
	v_mfma_f32_16x16x32_bf16 v[76:79], v[184:187], v[188:191], v[136:139]
	v_cvt_pk_bf16_f32 v39, v5, v17
	v_add_f32_e64 v64, v28, v64
	v_add_f32_e64 v65, v28, v65
	s_waitcnt vmcnt(16)
; __device__ __forceinline__ unsigned cvt_pk_bf16(float lo, float hi) { unsigned r; asm volatile("v_cvt_pk_bf16_f32 %0, %1, %2" : "=v"(r) : "v"(lo), "v"(hi)); return r; }
; __device__ __forceinline__ float bf_lo(unsigned w) { return __uint_as_float(w << 16); }
; __device__ __forceinline__ float bf_hi(unsigned w) { return __uint_as_float(w & 0xffff0000u); }
; __device__ __forceinline__ void mix_phase(const Params& p, LAS unsigned char* lds, int G, bool dry) {
;     ...
; #pragma unroll
;         for (int m = 0; m < 4; ++m) {
; #pragma unroll
;             for (int n = 0; n < 4; ++n) {
;                 const f32x4 a = acc[m][n] + bias[m]; const u32x2 u2 = ur[m][n];
;                 u32x2 w; w.x = cvt_pk_bf16(bf_lo(u2.x) * a[0], bf_hi(u2.x) * a[1]); w.y = cvt_pk_bf16(bf_lo(u2.y) * a[2], bf_hi(u2.y) * a[3]);
;                 if (!dry) *(u32x2*)(gup + (size_t)m * 16 * GW + 16 * n) = w;
;             }
;         }
;         if (tid == 0) misc[0] = nticket;
	v_lshlrev_b32_e32 v5, 16, v32
	v_mfma_f32_16x16x32_bf16 v[60:63], v[224:227], v[196:199], v[144:147]
	v_and_b32_e32 v17, 0xffff0000, v32
	v_mul_f32_e32 v5, v64, v5
	v_mul_f32_e32 v17, v65, v17
	global_store_dwordx2 v[22:23], v[38:39], off
	v_pk_add_f32 v[38:39], v[28:29], v[66:67] op_sel_hi:[0,1]
	v_cvt_pk_bf16_f32 v32, v5, v17
	v_lshlrev_b32_e32 v5, 16, v33
	v_and_b32_e32 v17, 0xffff0000, v33
	v_mul_f32_e32 v5, v38, v5
	v_mul_f32_e32 v17, v39, v17
	v_mfma_f32_16x16x32_bf16 v[136:139], v[168:171], v[200:203], v[140:143]
	v_cvt_pk_bf16_f32 v33, v5, v17
	s_waitcnt vmcnt(16)
	v_lshlrev_b32_e32 v5, 16, v30
	v_and_b32_e32 v17, 0xffff0000, v30
	v_mfma_f32_16x16x32_bf16 v[68:71], v[228:231], v[196:199], v[76:79]
	global_store_dwordx2 v[22:23], v[32:33], off offset:32
	v_pk_add_f32 v[32:33], v[28:29], v[62:63] op_sel_hi:[0,1]
	v_mfma_f32_16x16x32_bf16 v[38:41], v[224:227], v[212:215], v[40:43]
	s_nop 2
	v_add_f32_e64 v42, v28, v60
	v_add_f32_e64 v43, v28, v61
	v_mul_f32_e32 v5, v42, v5
	v_mul_f32_e32 v17, v43, v17
	v_cvt_pk_bf16_f32 v30, v5, v17
	v_lshlrev_b32_e32 v5, 16, v31
	v_and_b32_e32 v17, 0xffff0000, v31
	v_mul_f32_e32 v5, v32, v5
	v_mul_f32_e32 v17, v33, v17
	v_cvt_pk_bf16_f32 v31, v5, v17
	v_mfma_f32_16x16x32_bf16 v[140:143], v[172:175], v[200:203], v[152:155]
	global_store_dwordx2 v[22:23], v[30:31], off offset:64
	v_pk_add_f32 v[30:31], v[28:29], v[70:71] op_sel_hi:[0,1]
	v_pk_add_f32 v[28:29], v[28:29], v[68:69] op_sel_hi:[0,1]
	v_mfma_f32_16x16x32_bf16 v[72:75], v[216:219], v[204:207], v[136:139]
	s_waitcnt vmcnt(17)
	v_lshlrev_b32_e32 v5, 16, v26
	v_and_b32_e32 v17, 0xffff0000, v26
	v_mul_f32_e32 v5, v28, v5
	v_mul_f32_e32 v17, v29, v17
	v_cvt_pk_bf16_f32 v26, v5, v17
	v_lshlrev_b32_e32 v5, 16, v27
	v_and_b32_e32 v17, 0xffff0000, v27
	v_mul_f32_e32 v5, v30, v5
	v_mul_f32_e32 v17, v31, v17
	v_cvt_pk_bf16_f32 v27, v5, v17
	v_mfma_f32_16x16x32_bf16 v[132:135], v[176:179], v[200:203], v[164:167]
	global_store_dwordx2 v[22:23], v[26:27], off offset:96
	s_waitcnt vmcnt(17)
	v_pk_add_f32 v[22:23], v[16:17], v[74:75] op_sel_hi:[0,1]
	v_pk_add_f32 v[26:27], v[16:17], v[72:73] op_sel_hi:[0,1]
	v_mfma_f32_16x16x32_bf16 v[34:37], v[220:223], v[204:207], v[140:143]
	s_waitcnt vmcnt(16)
	v_lshlrev_b32_e32 v5, 16, v24
	v_and_b32_e32 v17, 0xffff0000, v24
	v_mul_f32_e32 v5, v26, v5
	v_mul_f32_e32 v17, v27, v17
	v_cvt_pk_bf16_f32 v24, v5, v17
	v_lshlrev_b32_e32 v5, 16, v25
	v_and_b32_e32 v17, 0xffff0000, v25
	v_mul_f32_e32 v5, v22, v5
	v_mul_f32_e32 v17, v23, v17
	v_cvt_pk_bf16_f32 v25, v5, v17
	v_mfma_f32_16x16x32_bf16 v[44:47], v[184:187], v[200:203], v[156:159]
	global_store_dwordx2 v[10:11], v[24:25], off
	v_pk_add_f32 v[22:23], v[16:17], v[36:37] op_sel_hi:[0,1]
	v_pk_add_f32 v[24:25], v[16:17], v[34:35] op_sel_hi:[0,1]
	v_mfma_f32_16x16x32_bf16 v[76:79], v[224:227], v[204:207], v[132:135]
	s_waitcnt vmcnt(16)
	v_lshlrev_b32_e32 v5, 16, v20
	v_and_b32_e32 v17, 0xffff0000, v20
	v_mul_f32_e32 v5, v24, v5
	v_mul_f32_e32 v17, v25, v17
	v_cvt_pk_bf16_f32 v20, v5, v17
	v_lshlrev_b32_e32 v5, 16, v21
	v_and_b32_e32 v17, 0xffff0000, v21
	v_mul_f32_e32 v5, v22, v5
	v_mul_f32_e32 v17, v23, v17
	v_cvt_pk_bf16_f32 v21, v5, v17
	v_mfma_f32_16x16x32_bf16 v[44:47], v[228:231], v[204:207], v[44:47]
	global_store_dwordx2 v[10:11], v[20:21], off offset:32
	v_pk_add_f32 v[20:21], v[16:17], v[78:79] op_sel_hi:[0,1]
	v_pk_add_f32 v[22:23], v[16:17], v[76:77] op_sel_hi:[0,1]
	s_waitcnt vmcnt(16)
	v_lshlrev_b32_e32 v5, 16, v18
	v_and_b32_e32 v17, 0xffff0000, v18
	v_mfma_f32_16x16x32_bf16 v[48:51], v[168:171], v[208:211], v[48:51]
	v_mul_f32_e32 v5, v22, v5
	v_mul_f32_e32 v17, v23, v17
	v_cvt_pk_bf16_f32 v18, v5, v17
	v_lshlrev_b32_e32 v5, 16, v19
	v_and_b32_e32 v17, 0xffff0000, v19
	v_mul_f32_e32 v5, v20, v5
	v_mul_f32_e32 v17, v21, v17
	v_cvt_pk_bf16_f32 v19, v5, v17
	global_store_dwordx2 v[10:11], v[18:19], off offset:64
	v_pk_add_f32 v[18:19], v[16:17], v[46:47] op_sel_hi:[0,1]
	v_pk_add_f32 v[16:17], v[16:17], v[44:45] op_sel_hi:[0,1]
	s_waitcnt vmcnt(16)
	v_lshlrev_b32_e32 v5, 16, v14
	v_and_b32_e32 v14, 0xffff0000, v14
	v_mfma_f32_16x16x32_bf16 v[48:51], v[216:219], v[212:215], v[48:51]
	v_mul_f32_e32 v5, v16, v5
	v_mul_f32_e32 v14, v17, v14
	v_cvt_pk_bf16_f32 v14, v5, v14
	v_mfma_f32_16x16x32_bf16 v[56:59], v[172:175], v[208:211], v[56:59]
	v_lshlrev_b32_e32 v5, 16, v15
	v_and_b32_e32 v15, 0xffff0000, v15
	v_mul_f32_e32 v15, v19, v15
	v_mul_f32_e32 v5, v18, v5
	v_cvt_pk_bf16_f32 v15, v5, v15
	global_store_dwordx2 v[10:11], v[14:15], off offset:96
	s_waitcnt vmcnt(16)
	v_pk_add_f32 v[10:11], v[4:5], v[50:51] op_sel_hi:[0,1]
	v_pk_add_f32 v[14:15], v[4:5], v[48:49] op_sel_hi:[0,1]
	s_waitcnt vmcnt(15)
	v_lshlrev_b32_e32 v5, 16, v12
	v_and_b32_e32 v12, 0xffff0000, v12
	v_mfma_f32_16x16x32_bf16 v[56:59], v[220:223], v[212:215], v[56:59]
	v_mul_f32_e32 v5, v14, v5
	v_mul_f32_e32 v12, v15, v12
	v_cvt_pk_bf16_f32 v12, v5, v12
	v_lshlrev_b32_e32 v5, 16, v13
	v_mul_f32_e32 v5, v10, v5
	v_and_b32_e32 v10, 0xffff0000, v13
	v_mul_f32_e32 v10, v11, v10
	v_cvt_pk_bf16_f32 v13, v5, v10
	global_store_dwordx2 v[0:1], v[12:13], off
	s_nop 0
	v_pk_add_f32 v[10:11], v[4:5], v[58:59] op_sel_hi:[0,1]
	v_pk_add_f32 v[12:13], v[4:5], v[56:57] op_sel_hi:[0,1]
	s_waitcnt vmcnt(15)
	v_lshlrev_b32_e32 v5, 16, v8
	v_and_b32_e32 v8, 0xffff0000, v8
	v_mul_f32_e32 v5, v12, v5
	v_mul_f32_e32 v8, v13, v8
	v_cvt_pk_bf16_f32 v8, v5, v8
	v_lshlrev_b32_e32 v5, 16, v9
	v_and_b32_e32 v9, 0xffff0000, v9
	v_mul_f32_e32 v9, v11, v9
	v_mul_f32_e32 v5, v10, v5
	v_cvt_pk_bf16_f32 v9, v5, v9
	global_store_dwordx2 v[0:1], v[8:9], off offset:32
	v_pk_add_f32 v[8:9], v[4:5], v[40:41] op_sel_hi:[0,1]
	v_pk_add_f32 v[10:11], v[4:5], v[38:39] op_sel_hi:[0,1]
	s_waitcnt vmcnt(15)
	v_lshlrev_b32_e32 v5, 16, v6
	v_and_b32_e32 v6, 0xffff0000, v6
	v_mfma_f32_16x16x32_bf16 v[52:55], v[228:231], v[212:215], v[52:55]
	v_mul_f32_e32 v5, v10, v5
	v_mul_f32_e32 v6, v11, v6
	v_cvt_pk_bf16_f32 v6, v5, v6
	v_lshlrev_b32_e32 v5, 16, v7
	v_and_b32_e32 v7, 0xffff0000, v7
	v_mul_f32_e32 v7, v9, v7
	v_mul_f32_e32 v5, v8, v5
	v_cvt_pk_bf16_f32 v7, v5, v7
	global_store_dwordx2 v[0:1], v[6:7], off offset:64
	s_nop 0
	v_pk_add_f32 v[6:7], v[4:5], v[54:55] op_sel_hi:[0,1]
	v_pk_add_f32 v[4:5], v[4:5], v[52:53] op_sel_hi:[0,1]
	s_waitcnt vmcnt(15)
	v_lshlrev_b32_e32 v8, 16, v2
	v_and_b32_e32 v2, 0xffff0000, v2
	v_mul_f32_e32 v4, v4, v8
	v_mul_f32_e32 v2, v5, v2
	v_cvt_pk_bf16_f32 v2, v4, v2
	v_lshlrev_b32_e32 v4, 16, v3
	v_and_b32_e32 v3, 0xffff0000, v3
	v_mul_f32_e32 v3, v7, v3
	v_mul_f32_e32 v4, v6, v4
	v_cvt_pk_bf16_f32 v3, v4, v3
	global_store_dwordx2 v[0:1], v[2:3], off offset:96
	s_and_saveexec_b64 s[10:11], s[12:13]
	s_xor_b64 s[10:11], exec, s[10:11]
	s_cbranch_execz .LBB0_157
	v_mov_b32_e32 v0, s33
	ds_write_b32 v0, v235
	s_branch .LBB0_157

; template <class Epi, class Sched, bool ALIGN_EPI = true>
; __device__ __forceinline__ void gemm_phase(LAS unsigned char* lds, const Gemm g, const Sched& S, const Epi& E) {
;     ...
;     f32x4 acc[2][2][4][2];
; #pragma unroll
;     for (int a = 0; a < 2; ++a)
; #pragma unroll
;         for (int b = 0; b < 2; ++b)
; #pragma unroll
;             for (int m = 0; m < 4; ++m)
; #pragma unroll
;                 for (int n = 0; n < 2; ++n) acc[a][b][m][n] = (f32x4){0.f, 0.f, 0.f, 0.f};
;     __device__ __forceinline__ void operator()(const f32x4 (&acc)[2][2][4][2], const pg8::Unit& u, int wr, int wc, int fr, int fq) const {
;     ...
;                 const int row = row0 + ai * 128 + m * 16;
;                 float* orow = oy + (size_t)row * DM + col0;
;                 const float* xr = FIRST ? ((row < MP ? xp + (size_t)row * DM : xs + (size_t)(row - MP) * DM) + col0) : orow;
;                 float q = 0.f;
; #pragma unroll
;                 for (int bj = 0; bj < 2; ++bj)
; #pragma unroll
;                     for (int n = 0; n < 2; ++n) {
;                         const f32x4 xv = *(const f32x4*)(xr + bj * 128 + n * 16);
.LBB0_293:
	s_ashr_i32 s9, s8, 31
	s_lshl_b64 s[38:39], s[8:9], 21
	s_add_u32 s38, s0, s38
	s_addc_u32 s39, s1, s39
	s_and_b64 s[40:41], s[36:37], exec
	s_cselect_b32 s9, s39, s43
	s_cselect_b32 s65, s38, s42
	s_ashr_i32 s35, s34, 31
	s_lshl_b64 s[40:41], s[34:35], 21
	s_add_u32 s40, s14, s40
	s_addc_u32 s41, s15, s41
	s_and_b64 s[48:49], s[36:37], exec
	s_cselect_b32 s35, s41, s45
	s_cselect_b32 s66, s40, s44
	s_add_u32 s67, s44, 0x100
	v_lshl_add_u64 v[140:141], s[42:43], 0, v[134:135]
	v_lshl_add_u64 v[142:143], s[42:43], 0, v[136:137]
	s_addc_u32 s68, s45, 0
	s_mov_b32 s69, -2
	s_mov_b64 s[44:45], 0
	v_mov_b32_e32 v144, s46
	s_waitcnt lgkmcnt(0)
	v_readlane_b32 s88, v234, 3
	v_readlane_b32 s89, v234, 4
	v_readlane_b32 s90, v234, 5
	v_readlane_b32 s91, v234, 6
	s_lshl_b32 s92, s63, 8
	s_cmp_lt_u32 s63, 32
	s_cselect_b32 s88, s88, s90
	s_cselect_b32 s89, s89, s91
	s_cselect_b32 s92, s92, 0
	v_add_u32_e32 v160, s92, v148
	v_mov_b32_e32 v161, 0
	v_lshlrev_b64 v[160:161], 13, v[160:161]
	v_lshl_or_b32 v162, s10, 8, v150
	v_mov_b32_e32 v163, 0
	v_lshl_add_u64 v[160:161], s[88:89], 0, v[160:161]
	v_lshl_add_u64 v[160:161], v[162:163], 2, v[160:161]
	global_load_dwordx4 v[124:127], v[160:161], off
	global_load_dwordx4 v[120:123], v[160:161], off offset:64
	global_load_dwordx4 v[116:119], v[160:161], off offset:512
	global_load_dwordx4 v[112:115], v[160:161], off offset:576
	s_mov_b64 s[88:89], 0x20000
	v_lshl_add_u64 v[166:167], v[160:161], 0, s[88:89]
	global_load_dwordx4 v[108:111], v[166:167], off
	global_load_dwordx4 v[104:107], v[166:167], off offset:64
	global_load_dwordx4 v[100:103], v[166:167], off offset:512
	global_load_dwordx4 v[96:99], v[166:167], off offset:576
	s_mov_b64 s[88:89], 0x40000
	v_lshl_add_u64 v[164:165], v[160:161], 0, s[88:89]
	global_load_dwordx4 v[92:95], v[164:165], off
	global_load_dwordx4 v[88:91], v[164:165], off offset:64
	global_load_dwordx4 v[84:87], v[164:165], off offset:512
	global_load_dwordx4 v[80:83], v[164:165], off offset:576
	s_mov_b64 s[88:89], 0x60000
	v_lshl_add_u64 v[166:167], v[160:161], 0, s[88:89]
	global_load_dwordx4 v[76:79], v[166:167], off
	global_load_dwordx4 v[72:75], v[166:167], off offset:64
	global_load_dwordx4 v[68:71], v[166:167], off offset:512
	global_load_dwordx4 v[64:67], v[166:167], off offset:576
	s_mov_b64 s[88:89], 0x100000
	v_lshl_add_u64 v[164:165], v[160:161], 0, s[88:89]
	global_load_dwordx4 v[60:63], v[164:165], off
	global_load_dwordx4 v[56:59], v[164:165], off offset:64
	global_load_dwordx4 v[52:55], v[164:165], off offset:512
	global_load_dwordx4 v[48:51], v[164:165], off offset:576
	s_mov_b64 s[88:89], 0x120000
	v_lshl_add_u64 v[166:167], v[160:161], 0, s[88:89]
	global_load_dwordx4 v[44:47], v[166:167], off
	global_load_dwordx4 v[40:43], v[166:167], off offset:64
	global_load_dwordx4 v[36:39], v[166:167], off offset:512
	global_load_dwordx4 v[32:35], v[166:167], off offset:576
	s_mov_b64 s[88:89], 0x140000
	v_lshl_add_u64 v[164:165], v[160:161], 0, s[88:89]
	global_load_dwordx4 v[28:31], v[164:165], off
	global_load_dwordx4 v[24:27], v[164:165], off offset:64
	global_load_dwordx4 v[20:23], v[164:165], off offset:512
	global_load_dwordx4 v[16:19], v[164:165], off offset:576
	s_mov_b64 s[88:89], 0x160000
	v_lshl_add_u64 v[166:167], v[160:161], 0, s[88:89]
	global_load_dwordx4 v[12:15], v[166:167], off
	global_load_dwordx4 v[8:11], v[166:167], off offset:64
	global_load_dwordx4 v[4:7], v[166:167], off offset:512
	global_load_dwordx4 v[0:3], v[166:167], off offset:576
	s_branch .LBB0_295

; __device__ __forceinline__ unsigned cvt_pk_bf16(float lo, float hi) { unsigned r; asm volatile("v_cvt_pk_bf16_f32 %0, %1, %2" : "=v"(r) : "v"(lo), "v"(hi)); return r; }
; __device__ __forceinline__ void st_wt8(void* ptr, u32x2 v) { asm volatile("global_store_dwordx2 %0, %1, off sc1" :: "v"(ptr), "v"(v) : "memory"); }
; __device__ __forceinline__ void st_wt4(void* ptr, unsigned v) { asm volatile("global_store_dword %0, %1, off sc1" :: "v"(ptr), "v"(v) : "memory"); }
;     __device__ __forceinline__ void operator()(const f32x4 (&acc)[2][2][4][2], const pg8::Unit& u, int wr, int wc, int fr, int fq) const {
;     ...
;         for (int ai = 0; ai < 2; ++ai)
; #pragma unroll
;             for (int m = 0; m < 4; ++m) {
;                 const int row = row0 + ai * 128 + m * 16;
;                 float* orow = oy + (size_t)row * DM + col0;
;                 const float* xr = FIRST ? ((row < MP ? xp + (size_t)row * DM : xs + (size_t)(row - MP) * DM) + col0) : orow;
;                 float q = 0.f;
; #pragma unroll
;                 for (int bj = 0; bj < 2; ++bj)
; #pragma unroll
;                     for (int n = 0; n < 2; ++n) {
;                         const f32x4 xv = *(const f32x4*)(xr + bj * 128 + n * 16);
;                         const f32x4 o = xv + acc[ai][bj][m][n];
;                         *(f32x4*)(orow + bj * 128 + n * 16) = o;
;                         q += (o[0] * o[0] + o[1] * o[1]) + (o[2] * o[2] + o[3] * o[3]);
;                         if (FIRST) { u32x2 w; w.x = cvt_pk_bf16(o[0], o[1]); w.y = cvt_pk_bf16(o[2], o[3]); st_wt8(xb + (size_t)row * DM + col0 + bj * 128 + n * 16, w); }
;                     }
;                 q += __shfl_xor(q, 16); q += __shfl_xor(q, 32);
;                 if (fq == 0) { if (FIRST) st_wt4(ss + (size_t)row * 32 + u.pn * 4 + wc, __float_as_uint(q)); else ss[(size_t)row * 32 + u.pn * 4 + wc] = q; }
.LBB0_299:
	v_mbcnt_lo_u32_b32 v240, -1, 0
	v_mbcnt_hi_u32_b32 v240, -1, v240
	v_lshrrev_b32_e32 v240, 4, v240
	v_lshlrev_b32_e32 v240, 3, v240
	v_add_u32_e32 v240, 0xffffffe0, v240
	v_mov_b32_e32 v241, -1
	v_lshl_add_u32 v144, s63, 8, v148
	v_ashrrev_i32_e32 v145, 31, v144
	v_readlane_b32 s68, v234, 3
	v_add_u32_e32 v132, 0xffffe000, v144
	v_lshl_or_b32 v140, s10, 8, v150
	v_lshlrev_b64 v[156:157], 13, v[144:145]
	v_readlane_b32 s69, v234, 4
	v_readlane_b32 s70, v234, 5
	v_readlane_b32 s71, v234, 6
	v_lshlrev_b64 v[154:155], 13, v[132:133]
	v_ashrrev_i32_e32 v141, 31, v140
	v_lshl_add_u64 v[152:153], s[68:69], 0, v[156:157]
	v_lshl_add_u64 v[154:155], s[70:71], 0, v[154:155]
	v_cmp_gt_i32_e32 vcc, s54, v144
	v_lshlrev_b64 v[142:143], 2, v[140:141]
	v_lshlrev_b64 v[160:161], 12, v[144:145]
	v_cndmask_b32_e32 v153, v155, v153, vcc
	v_cndmask_b32_e32 v152, v154, v152, vcc
	v_lshl_add_u64 v[158:159], v[152:153], 0, v[142:143]
	v_mov_b32_e32 v152, 0
	v_mov_b32_e32 v153, 0
	v_mov_b32_e32 v154, 0
	v_mov_b32_e32 v155, 0
	v_lshl_add_u64 v[156:157], s[84:85], 0, v[156:157]
	v_lshl_add_u64 v[160:161], s[20:21], 0, v[160:161]
	v_lshl_add_u64 v[162:163], v[156:157], 0, v[142:143]
	v_lshl_add_u64 v[160:161], v[140:141], 1, v[160:161]
	v_lshl_add_u64 v[156:157], v[160:161], 0, 32
	s_lshl_b32 s42, s10, 2
	s_ashr_i32 s43, s42, 31
	v_readlane_b32 s72, v234, 7
	v_readlane_b32 s73, v234, 8
	v_readlane_b32 s74, v234, 9
	v_readlane_b32 s75, v234, 10
	v_readlane_b32 s76, v234, 11
	v_readlane_b32 s77, v234, 12
	v_readlane_b32 s78, v234, 13
	v_readlane_b32 s79, v234, 14
	v_readlane_b32 s80, v234, 15
	v_readlane_b32 s81, v234, 16
	v_readlane_b32 s82, v234, 17
	v_readlane_b32 s83, v234, 18
	v_pk_add_f32 v[126:127], v[126:127], v[154:155]
	v_pk_add_f32 v[124:125], v[124:125], v[152:153]
	global_store_dwordx4 v[162:163], v[124:127], off
	v_cvt_pk_bf16_f32 v236, v124, v125
	v_cvt_pk_bf16_f32 v237, v126, v127
	s_nop 0
	v_mov_b32_e32 v152, 0
	v_mov_b32_e32 v153, 0
	v_mov_b32_e32 v154, 0
	v_mov_b32_e32 v155, 0
	v_pk_add_f32 v[122:123], v[122:123], v[154:155]
	v_pk_add_f32 v[120:121], v[120:121], v[152:153]
	global_store_dwordx4 v[162:163], v[120:123], off offset:64
	v_cvt_pk_bf16_f32 v238, v120, v121
	v_cvt_pk_bf16_f32 v239, v122, v123
	s_nop 0
	s_nop 1
	v_permlane32_swap_b32_e32 v236, v238
	v_permlane32_swap_b32_e32 v237, v239
	s_nop 1
	v_permlane16_swap_b32_e32 v236, v238
	v_permlane16_swap_b32_e32 v237, v239
	v_lshl_add_u64 v[242:243], v[156:157], 0, v[240:241]
	s_nop 0
	global_store_dwordx4 v[242:243], v[236:239], off sc1
	s_nop 1
	v_mov_b32_e32 v152, 0
	v_mov_b32_e32 v153, 0
	v_mov_b32_e32 v154, 0
	v_mov_b32_e32 v155, 0
	v_lshl_add_u64 v[156:157], v[160:161], 0, s[28:29]
	v_pk_add_f32 v[154:155], v[118:119], v[154:155]
	v_pk_add_f32 v[152:153], v[116:117], v[152:153]
	global_store_dwordx4 v[162:163], v[152:155], off offset:512
	v_cvt_pk_bf16_f32 v236, v152, v153
	v_cvt_pk_bf16_f32 v237, v154, v155
	v_xor_b32_e32 v118, 32, v195
	v_mov_b32_e32 v156, 0
	v_mov_b32_e32 v157, 0
	v_mov_b32_e32 v158, 0
	v_mov_b32_e32 v159, 0
	v_and_b32_e32 v117, 64, v195
	v_xor_b32_e32 v116, 16, v195
	v_add_u32_e32 v117, 64, v117
	v_cmp_lt_i32_e32 vcc, v116, v117
	v_mul_f32_e32 v119, v127, v127
	v_fmac_f32_e32 v119, v126, v126
	v_cndmask_b32_e32 v116, v195, v116, vcc
	v_cmp_lt_i32_e32 vcc, v118, v117
	v_lshlrev_b32_e32 v116, 2, v116
	v_pk_add_f32 v[114:115], v[114:115], v[158:159]
	v_cndmask_b32_e32 v117, v195, v118, vcc
	v_mul_f32_e32 v118, v125, v125
	v_fmac_f32_e32 v118, v124, v124
	v_add_f32_e32 v118, v118, v119
	v_mul_f32_e32 v119, v121, v121
	v_mul_f32_e32 v121, v123, v123
	v_fmac_f32_e32 v119, v120, v120
	v_fmac_f32_e32 v121, v122, v122
	v_add_f32_e32 v119, v119, v121
	v_add_f32_e32 v118, v118, v119
	v_mul_f32_e32 v119, v153, v153
	v_mul_f32_e32 v120, v155, v155
	v_fmac_f32_e32 v119, v152, v152
	v_fmac_f32_e32 v120, v154, v154
	v_add_f32_e32 v119, v119, v120
	v_pk_add_f32 v[112:113], v[112:113], v[156:157]
	v_add_f32_e32 v118, v118, v119
	v_mul_f32_e32 v119, v113, v113
	v_mul_f32_e32 v120, v115, v115
	v_fmac_f32_e32 v119, v112, v112
	v_fmac_f32_e32 v120, v114, v114
	v_add_f32_e32 v119, v119, v120
	v_add_f32_e32 v122, v118, v119
	ds_bpermute_b32 v123, v116, v122
	global_store_dwordx4 v[162:163], v[112:115], off offset:576
	v_cvt_pk_bf16_f32 v238, v112, v113
	v_cvt_pk_bf16_f32 v239, v114, v115
	v_lshl_add_u64 v[118:119], v[160:161], 0, s[30:31]
	s_nop 1
	v_permlane32_swap_b32_e32 v236, v238
	v_permlane32_swap_b32_e32 v237, v239
	s_nop 1
	v_permlane16_swap_b32_e32 v236, v238
	v_permlane16_swap_b32_e32 v237, v239
	v_lshl_add_u64 v[242:243], v[118:119], 0, v[240:241]
	s_nop 0
	global_store_dwordx4 v[242:243], v[236:239], off sc1
	s_nop 1
	s_waitcnt lgkmcnt(0)
	v_add_f32_e32 v112, v122, v123
	v_lshlrev_b32_e32 v114, 2, v117
	ds_bpermute_b32 v113, v114, v112
	s_and_saveexec_b64 s[44:45], s[4:5]
	s_cbranch_execz .LBB0_301
	s_waitcnt lgkmcnt(0)
	v_add_f32_e32 v115, v112, v113
	v_lshlrev_b64 v[112:113], 7, v[144:145]
	v_lshl_add_u64 v[112:113], s[2:3], 0, v[112:113]
	v_lshl_add_u64 v[112:113], s[42:43], 2, v[112:113]
	s_lshl_b32 s10, s55, 2
	v_lshl_add_u64 v[112:113], v[112:113], 0, s[10:11]
	global_store_dword v[112:113], v115, off sc1
; __device__ __forceinline__ unsigned cvt_pk_bf16(float lo, float hi) { unsigned r; asm volatile("v_cvt_pk_bf16_f32 %0, %1, %2" : "=v"(r) : "v"(lo), "v"(hi)); return r; }
; __device__ __forceinline__ void st_wt8(void* ptr, u32x2 v) { asm volatile("global_store_dwordx2 %0, %1, off sc1" :: "v"(ptr), "v"(v) : "memory"); }
; __device__ __forceinline__ void st_wt4(void* ptr, unsigned v) { asm volatile("global_store_dword %0, %1, off sc1" :: "v"(ptr), "v"(v) : "memory"); }
;     __device__ __forceinline__ void operator()(const f32x4 (&acc)[2][2][4][2], const pg8::Unit& u, int wr, int wc, int fr, int fq) const {
;     ...
;         for (int ai = 0; ai < 2; ++ai)
; #pragma unroll
;             for (int m = 0; m < 4; ++m) {
;                 const int row = row0 + ai * 128 + m * 16;
;                 float* orow = oy + (size_t)row * DM + col0;
;                 const float* xr = FIRST ? ((row < MP ? xp + (size_t)row * DM : xs + (size_t)(row - MP) * DM) + col0) : orow;
;                 float q = 0.f;
; #pragma unroll
;                 for (int bj = 0; bj < 2; ++bj)
; #pragma unroll
;                     for (int n = 0; n < 2; ++n) {
;                         const f32x4 xv = *(const f32x4*)(xr + bj * 128 + n * 16);
;                         const f32x4 o = xv + acc[ai][bj][m][n];
;                         *(f32x4*)(orow + bj * 128 + n * 16) = o;
;                         q += (o[0] * o[0] + o[1] * o[1]) + (o[2] * o[2] + o[3] * o[3]);
;                         if (FIRST) { u32x2 w; w.x = cvt_pk_bf16(o[0], o[1]); w.y = cvt_pk_bf16(o[2], o[3]); st_wt8(xb + (size_t)row * DM + col0 + bj * 128 + n * 16, w); }
;                     }
;                 q += __shfl_xor(q, 16); q += __shfl_xor(q, 32);
;                 if (fq == 0) { if (FIRST) st_wt4(ss + (size_t)row * 32 + u.pn * 4 + wc, __float_as_uint(q)); else ss[(size_t)row * 32 + u.pn * 4 + wc] = q; }
.LBB0_301:
	s_or_b64 exec, exec, s[44:45]
	v_or_b32_e32 v112, 16, v144
	s_waitcnt lgkmcnt(0)
	v_ashrrev_i32_e32 v113, 31, v112
	v_readlane_b32 s68, v234, 3
	v_add_u32_e32 v132, 0xffffe010, v144
	v_lshlrev_b64 v[122:123], 13, v[112:113]
	v_readlane_b32 s69, v234, 4
	v_readlane_b32 s70, v234, 5
	v_readlane_b32 s71, v234, 6
	v_lshlrev_b64 v[120:121], 13, v[132:133]
	v_lshl_add_u64 v[118:119], s[68:69], 0, v[122:123]
	v_lshl_add_u64 v[120:121], s[70:71], 0, v[120:121]
	v_cmp_gt_i32_e32 vcc, s54, v112
	v_lshlrev_b64 v[126:127], 12, v[112:113]
	v_lshl_add_u64 v[122:123], s[84:85], 0, v[122:123]
	v_cndmask_b32_e32 v119, v121, v119, vcc
	v_cndmask_b32_e32 v118, v120, v118, vcc
	v_lshl_add_u64 v[124:125], v[118:119], 0, v[142:143]
	v_mov_b32_e32 v118, 0
	v_mov_b32_e32 v119, 0
	v_mov_b32_e32 v120, 0
	v_mov_b32_e32 v121, 0
	v_lshl_add_u64 v[126:127], s[20:21], 0, v[126:127]
	v_lshl_add_u64 v[122:123], v[122:123], 0, v[142:143]
	v_lshl_add_u64 v[126:127], v[140:141], 1, v[126:127]
	v_lshl_add_u64 v[152:153], v[126:127], 0, 32
	v_readlane_b32 s72, v234, 7
	v_readlane_b32 s73, v234, 8
	v_readlane_b32 s74, v234, 9
	v_readlane_b32 s75, v234, 10
	v_readlane_b32 s76, v234, 11
	v_readlane_b32 s77, v234, 12
	v_readlane_b32 s78, v234, 13
	v_readlane_b32 s79, v234, 14
	v_readlane_b32 s80, v234, 15
	v_readlane_b32 s81, v234, 16
	v_readlane_b32 s82, v234, 17
	v_readlane_b32 s83, v234, 18
	v_pk_add_f32 v[110:111], v[110:111], v[120:121]
	v_pk_add_f32 v[108:109], v[108:109], v[118:119]
	global_store_dwordx4 v[122:123], v[108:111], off
	v_cvt_pk_bf16_f32 v236, v108, v109
	v_cvt_pk_bf16_f32 v237, v110, v111
	s_nop 0
	v_mov_b32_e32 v118, 0
	v_mov_b32_e32 v119, 0
	v_mov_b32_e32 v120, 0
	v_mov_b32_e32 v121, 0
	v_mul_f32_e32 v109, v109, v109
	v_mul_f32_e32 v111, v111, v111
	v_fmac_f32_e32 v109, v108, v108
	v_fmac_f32_e32 v111, v110, v110
	v_add_f32_e32 v108, v109, v111
	v_pk_add_f32 v[106:107], v[106:107], v[120:121]
	v_pk_add_f32 v[104:105], v[104:105], v[118:119]
	global_store_dwordx4 v[122:123], v[104:107], off offset:64
	v_cvt_pk_bf16_f32 v238, v104, v105
	v_cvt_pk_bf16_f32 v239, v106, v107
	s_nop 0
	s_nop 1
	v_permlane32_swap_b32_e32 v236, v238
	v_permlane32_swap_b32_e32 v237, v239
	s_nop 1
	v_permlane16_swap_b32_e32 v236, v238
	v_permlane16_swap_b32_e32 v237, v239
	v_lshl_add_u64 v[242:243], v[152:153], 0, v[240:241]
	s_nop 0
	global_store_dwordx4 v[242:243], v[236:239], off sc1
	s_nop 1
	v_mov_b32_e32 v118, 0
	v_mov_b32_e32 v119, 0
	v_mov_b32_e32 v120, 0
	v_mov_b32_e32 v121, 0
	v_lshl_add_u64 v[152:153], v[126:127], 0, s[28:29]
	v_mul_f32_e32 v105, v105, v105
	v_mul_f32_e32 v107, v107, v107
	v_fmac_f32_e32 v105, v104, v104
	v_fmac_f32_e32 v107, v106, v106
	v_add_f32_e32 v104, v105, v107
	v_add_f32_e32 v104, v108, v104
	v_pk_add_f32 v[102:103], v[102:103], v[120:121]
	v_pk_add_f32 v[100:101], v[100:101], v[118:119]
	global_store_dwordx4 v[122:123], v[100:103], off offset:512
	v_cvt_pk_bf16_f32 v236, v100, v101
	v_cvt_pk_bf16_f32 v237, v102, v103
	s_nop 0
	v_mov_b32_e32 v118, 0
	v_mov_b32_e32 v119, 0
	v_mov_b32_e32 v120, 0
	v_mov_b32_e32 v121, 0
	v_mul_f32_e32 v101, v101, v101
	v_mul_f32_e32 v103, v103, v103
	v_fmac_f32_e32 v101, v100, v100
	v_fmac_f32_e32 v103, v102, v102
	v_add_f32_e32 v100, v101, v103
	v_add_f32_e32 v100, v104, v100
	v_pk_add_f32 v[98:99], v[98:99], v[120:121]
	v_pk_add_f32 v[96:97], v[96:97], v[118:119]
	v_mul_f32_e32 v102, v99, v99
	v_mul_f32_e32 v101, v97, v97
	v_fmac_f32_e32 v101, v96, v96
	v_fmac_f32_e32 v102, v98, v98
	v_add_f32_e32 v101, v101, v102
	v_add_f32_e32 v102, v100, v101
	ds_bpermute_b32 v103, v116, v102
	global_store_dwordx4 v[122:123], v[96:99], off offset:576
	v_cvt_pk_bf16_f32 v238, v96, v97
	v_cvt_pk_bf16_f32 v239, v98, v99
	s_waitcnt lgkmcnt(0)
	s_nop 0
	v_add_f32_e32 v96, v102, v103
	ds_bpermute_b32 v97, v114, v96
	v_lshl_add_u64 v[98:99], v[126:127], 0, s[30:31]
	s_nop 1
	v_permlane32_swap_b32_e32 v236, v238
	v_permlane32_swap_b32_e32 v237, v239
	s_nop 1
	v_permlane16_swap_b32_e32 v236, v238
	v_permlane16_swap_b32_e32 v237, v239
	v_lshl_add_u64 v[242:243], v[98:99], 0, v[240:241]
	s_nop 0
	global_store_dwordx4 v[242:243], v[236:239], off sc1
	s_nop 1
	s_and_saveexec_b64 s[44:45], s[4:5]
	s_cbranch_execz .LBB0_303
	s_waitcnt lgkmcnt(0)
	v_add_f32_e32 v98, v96, v97
	v_lshlrev_b64 v[96:97], 7, v[112:113]
	v_lshl_add_u64 v[96:97], s[2:3], 0, v[96:97]
	v_lshl_add_u64 v[96:97], s[42:43], 2, v[96:97]
	s_lshl_b32 s10, s55, 2
	v_lshl_add_u64 v[96:97], v[96:97], 0, s[10:11]
	global_store_dword v[96:97], v98, off sc1
; __device__ __forceinline__ unsigned cvt_pk_bf16(float lo, float hi) { unsigned r; asm volatile("v_cvt_pk_bf16_f32 %0, %1, %2" : "=v"(r) : "v"(lo), "v"(hi)); return r; }
; __device__ __forceinline__ void st_wt8(void* ptr, u32x2 v) { asm volatile("global_store_dwordx2 %0, %1, off sc1" :: "v"(ptr), "v"(v) : "memory"); }
; __device__ __forceinline__ void st_wt4(void* ptr, unsigned v) { asm volatile("global_store_dword %0, %1, off sc1" :: "v"(ptr), "v"(v) : "memory"); }
;     __device__ __forceinline__ void operator()(const f32x4 (&acc)[2][2][4][2], const pg8::Unit& u, int wr, int wc, int fr, int fq) const {
;     ...
;                 const int row = row0 + ai * 128 + m * 16;
;                 float* orow = oy + (size_t)row * DM + col0;
;                 const float* xr = FIRST ? ((row < MP ? xp + (size_t)row * DM : xs + (size_t)(row - MP) * DM) + col0) : orow;
;                 float q = 0.f;
; #pragma unroll
;                 for (int bj = 0; bj < 2; ++bj)
; #pragma unroll
;                     for (int n = 0; n < 2; ++n) {
;                         const f32x4 xv = *(const f32x4*)(xr + bj * 128 + n * 16);
;                         const f32x4 o = xv + acc[ai][bj][m][n];
;                         *(f32x4*)(orow + bj * 128 + n * 16) = o;
;                         q += (o[0] * o[0] + o[1] * o[1]) + (o[2] * o[2] + o[3] * o[3]);
;                         if (FIRST) { u32x2 w; w.x = cvt_pk_bf16(o[0], o[1]); w.y = cvt_pk_bf16(o[2], o[3]); st_wt8(xb + (size_t)row * DM + col0 + bj * 128 + n * 16, w); }
;                     }
;                 q += __shfl_xor(q, 16); q += __shfl_xor(q, 32);
;                 if (fq == 0) { if (FIRST) st_wt4(ss + (size_t)row * 32 + u.pn * 4 + wc, __float_as_uint(q)); else ss[(size_t)row * 32 + u.pn * 4 + wc] = q; }
.LBB0_303:
	s_or_b64 exec, exec, s[44:45]
	v_or_b32_e32 v96, 32, v144
	s_waitcnt lgkmcnt(0)
	v_ashrrev_i32_e32 v97, 31, v96
	v_readlane_b32 s68, v234, 3
	v_add_u32_e32 v132, 0xffffe020, v144
	v_lshlrev_b64 v[102:103], 13, v[96:97]
	v_readlane_b32 s69, v234, 4
	v_readlane_b32 s70, v234, 5
	v_readlane_b32 s71, v234, 6
	v_lshlrev_b64 v[100:101], 13, v[132:133]
	v_lshl_add_u64 v[98:99], s[68:69], 0, v[102:103]
	v_lshl_add_u64 v[100:101], s[70:71], 0, v[100:101]
	v_cmp_gt_i32_e32 vcc, s54, v96
	v_lshlrev_b64 v[106:107], 12, v[96:97]
	v_lshl_add_u64 v[102:103], s[84:85], 0, v[102:103]
	v_cndmask_b32_e32 v99, v101, v99, vcc
	v_cndmask_b32_e32 v98, v100, v98, vcc
	v_lshl_add_u64 v[104:105], v[98:99], 0, v[142:143]
	v_mov_b32_e32 v98, 0
	v_mov_b32_e32 v99, 0
	v_mov_b32_e32 v100, 0
	v_mov_b32_e32 v101, 0
	v_lshl_add_u64 v[106:107], s[20:21], 0, v[106:107]
	v_lshl_add_u64 v[102:103], v[102:103], 0, v[142:143]
	v_lshl_add_u64 v[106:107], v[140:141], 1, v[106:107]
	v_lshl_add_u64 v[108:109], v[106:107], 0, 32
	v_readlane_b32 s72, v234, 7
	v_readlane_b32 s73, v234, 8
	v_readlane_b32 s74, v234, 9
	v_readlane_b32 s75, v234, 10
	v_readlane_b32 s76, v234, 11
	v_readlane_b32 s77, v234, 12
	v_readlane_b32 s78, v234, 13
	v_readlane_b32 s79, v234, 14
	v_readlane_b32 s80, v234, 15
	v_readlane_b32 s81, v234, 16
	v_readlane_b32 s82, v234, 17
	v_readlane_b32 s83, v234, 18
	v_pk_add_f32 v[94:95], v[94:95], v[100:101]
	v_pk_add_f32 v[92:93], v[92:93], v[98:99]
	global_store_dwordx4 v[102:103], v[92:95], off
	v_cvt_pk_bf16_f32 v236, v92, v93
	v_cvt_pk_bf16_f32 v237, v94, v95
	s_nop 0
	v_mov_b32_e32 v98, 0
	v_mov_b32_e32 v99, 0
	v_mov_b32_e32 v100, 0
	v_mov_b32_e32 v101, 0
	v_mul_f32_e32 v93, v93, v93
	v_mul_f32_e32 v95, v95, v95
	v_fmac_f32_e32 v93, v92, v92
	v_fmac_f32_e32 v95, v94, v94
	v_add_f32_e32 v92, v93, v95
	v_pk_add_f32 v[90:91], v[90:91], v[100:101]
	v_pk_add_f32 v[88:89], v[88:89], v[98:99]
	global_store_dwordx4 v[102:103], v[88:91], off offset:64
	v_cvt_pk_bf16_f32 v238, v88, v89
	v_cvt_pk_bf16_f32 v239, v90, v91
	s_nop 0
	s_nop 1
	v_permlane32_swap_b32_e32 v236, v238
	v_permlane32_swap_b32_e32 v237, v239
	s_nop 1
	v_permlane16_swap_b32_e32 v236, v238
	v_permlane16_swap_b32_e32 v237, v239
	v_lshl_add_u64 v[242:243], v[108:109], 0, v[240:241]
	s_nop 0
	global_store_dwordx4 v[242:243], v[236:239], off sc1
	s_nop 1
	v_mov_b32_e32 v98, 0
	v_mov_b32_e32 v99, 0
	v_mov_b32_e32 v100, 0
	v_mov_b32_e32 v101, 0
	v_lshl_add_u64 v[108:109], v[106:107], 0, s[28:29]
	v_mul_f32_e32 v89, v89, v89
	v_mul_f32_e32 v91, v91, v91
	v_fmac_f32_e32 v89, v88, v88
	v_fmac_f32_e32 v91, v90, v90
	v_add_f32_e32 v88, v89, v91
	v_add_f32_e32 v88, v92, v88
	v_pk_add_f32 v[86:87], v[86:87], v[100:101]
	v_pk_add_f32 v[84:85], v[84:85], v[98:99]
	global_store_dwordx4 v[102:103], v[84:87], off offset:512
	v_cvt_pk_bf16_f32 v236, v84, v85
	v_cvt_pk_bf16_f32 v237, v86, v87
	s_nop 0
	v_mov_b32_e32 v98, 0
	v_mov_b32_e32 v99, 0
	v_mov_b32_e32 v100, 0
	v_mov_b32_e32 v101, 0
	v_mul_f32_e32 v85, v85, v85
	v_mul_f32_e32 v87, v87, v87
	v_fmac_f32_e32 v85, v84, v84
	v_fmac_f32_e32 v87, v86, v86
	v_add_f32_e32 v84, v85, v87
	v_add_f32_e32 v84, v88, v84
	v_pk_add_f32 v[82:83], v[82:83], v[100:101]
	v_pk_add_f32 v[80:81], v[80:81], v[98:99]
	v_mul_f32_e32 v86, v83, v83
	v_mul_f32_e32 v85, v81, v81
	v_fmac_f32_e32 v85, v80, v80
	v_fmac_f32_e32 v86, v82, v82
	v_add_f32_e32 v85, v85, v86
	v_add_f32_e32 v86, v84, v85
	ds_bpermute_b32 v87, v116, v86
	global_store_dwordx4 v[102:103], v[80:83], off offset:576
	v_cvt_pk_bf16_f32 v238, v80, v81
	v_cvt_pk_bf16_f32 v239, v82, v83
	s_waitcnt lgkmcnt(0)
	s_nop 0
	v_add_f32_e32 v80, v86, v87
	ds_bpermute_b32 v81, v114, v80
	v_lshl_add_u64 v[82:83], v[106:107], 0, s[30:31]
	s_nop 1
	v_permlane32_swap_b32_e32 v236, v238
	v_permlane32_swap_b32_e32 v237, v239
	s_nop 1
	v_permlane16_swap_b32_e32 v236, v238
	v_permlane16_swap_b32_e32 v237, v239
	v_lshl_add_u64 v[242:243], v[82:83], 0, v[240:241]
	s_nop 0
	global_store_dwordx4 v[242:243], v[236:239], off sc1
	s_nop 1
	s_and_saveexec_b64 s[44:45], s[4:5]
	s_cbranch_execz .LBB0_305
	s_waitcnt lgkmcnt(0)
	v_add_f32_e32 v82, v80, v81
	v_lshlrev_b64 v[80:81], 7, v[96:97]
	v_lshl_add_u64 v[80:81], s[2:3], 0, v[80:81]
	v_lshl_add_u64 v[80:81], s[42:43], 2, v[80:81]
	s_lshl_b32 s10, s55, 2
	v_lshl_add_u64 v[80:81], v[80:81], 0, s[10:11]
	global_store_dword v[80:81], v82, off sc1
; __device__ __forceinline__ unsigned cvt_pk_bf16(float lo, float hi) { unsigned r; asm volatile("v_cvt_pk_bf16_f32 %0, %1, %2" : "=v"(r) : "v"(lo), "v"(hi)); return r; }
; __device__ __forceinline__ void st_wt8(void* ptr, u32x2 v) { asm volatile("global_store_dwordx2 %0, %1, off sc1" :: "v"(ptr), "v"(v) : "memory"); }
; __device__ __forceinline__ void st_wt4(void* ptr, unsigned v) { asm volatile("global_store_dword %0, %1, off sc1" :: "v"(ptr), "v"(v) : "memory"); }
;     __device__ __forceinline__ void operator()(const f32x4 (&acc)[2][2][4][2], const pg8::Unit& u, int wr, int wc, int fr, int fq) const {
;     ...
;                 const int row = row0 + ai * 128 + m * 16;
;                 float* orow = oy + (size_t)row * DM + col0;
;                 const float* xr = FIRST ? ((row < MP ? xp + (size_t)row * DM : xs + (size_t)(row - MP) * DM) + col0) : orow;
;                 float q = 0.f;
; #pragma unroll
;                 for (int bj = 0; bj < 2; ++bj)
; #pragma unroll
;                     for (int n = 0; n < 2; ++n) {
;                         const f32x4 xv = *(const f32x4*)(xr + bj * 128 + n * 16);
;                         const f32x4 o = xv + acc[ai][bj][m][n];
;                         *(f32x4*)(orow + bj * 128 + n * 16) = o;
;                         q += (o[0] * o[0] + o[1] * o[1]) + (o[2] * o[2] + o[3] * o[3]);
;                         if (FIRST) { u32x2 w; w.x = cvt_pk_bf16(o[0], o[1]); w.y = cvt_pk_bf16(o[2], o[3]); st_wt8(xb + (size_t)row * DM + col0 + bj * 128 + n * 16, w); }
;                     }
;                 q += __shfl_xor(q, 16); q += __shfl_xor(q, 32);
;                 if (fq == 0) { if (FIRST) st_wt4(ss + (size_t)row * 32 + u.pn * 4 + wc, __float_as_uint(q)); else ss[(size_t)row * 32 + u.pn * 4 + wc] = q; }
.LBB0_305:
	s_or_b64 exec, exec, s[44:45]
	v_or_b32_e32 v80, 48, v144
	s_waitcnt lgkmcnt(0)
	v_ashrrev_i32_e32 v81, 31, v80
	v_readlane_b32 s68, v234, 3
	v_add_u32_e32 v132, 0xffffe030, v144
	v_lshlrev_b64 v[86:87], 13, v[80:81]
	v_readlane_b32 s69, v234, 4
	v_readlane_b32 s70, v234, 5
	v_readlane_b32 s71, v234, 6
	v_lshlrev_b64 v[84:85], 13, v[132:133]
	v_lshl_add_u64 v[82:83], s[68:69], 0, v[86:87]
	v_lshl_add_u64 v[84:85], s[70:71], 0, v[84:85]
	v_cmp_gt_i32_e32 vcc, s54, v80
	v_lshlrev_b64 v[90:91], 12, v[80:81]
	v_lshl_add_u64 v[86:87], s[84:85], 0, v[86:87]
	v_cndmask_b32_e32 v83, v85, v83, vcc
	v_cndmask_b32_e32 v82, v84, v82, vcc
	v_lshl_add_u64 v[88:89], v[82:83], 0, v[142:143]
	v_mov_b32_e32 v82, 0
	v_mov_b32_e32 v83, 0
	v_mov_b32_e32 v84, 0
	v_mov_b32_e32 v85, 0
	v_lshl_add_u64 v[90:91], s[20:21], 0, v[90:91]
	v_lshl_add_u64 v[86:87], v[86:87], 0, v[142:143]
	v_lshl_add_u64 v[90:91], v[140:141], 1, v[90:91]
	v_lshl_add_u64 v[92:93], v[90:91], 0, 32
	v_readlane_b32 s72, v234, 7
	v_readlane_b32 s73, v234, 8
	v_readlane_b32 s74, v234, 9
	v_readlane_b32 s75, v234, 10
	v_readlane_b32 s76, v234, 11
	v_readlane_b32 s77, v234, 12
	v_readlane_b32 s78, v234, 13
	v_readlane_b32 s79, v234, 14
	v_readlane_b32 s80, v234, 15
	v_readlane_b32 s81, v234, 16
	v_readlane_b32 s82, v234, 17
	v_readlane_b32 s83, v234, 18
	v_pk_add_f32 v[78:79], v[78:79], v[84:85]
	v_pk_add_f32 v[76:77], v[76:77], v[82:83]
	global_store_dwordx4 v[86:87], v[76:79], off
	v_cvt_pk_bf16_f32 v236, v76, v77
	v_cvt_pk_bf16_f32 v237, v78, v79
	s_nop 0
	v_mov_b32_e32 v82, 0
	v_mov_b32_e32 v83, 0
	v_mov_b32_e32 v84, 0
	v_mov_b32_e32 v85, 0
	v_mul_f32_e32 v77, v77, v77
	v_mul_f32_e32 v79, v79, v79
	v_fmac_f32_e32 v77, v76, v76
	v_fmac_f32_e32 v79, v78, v78
	v_add_f32_e32 v76, v77, v79
	v_pk_add_f32 v[74:75], v[74:75], v[84:85]
	v_pk_add_f32 v[72:73], v[72:73], v[82:83]
	global_store_dwordx4 v[86:87], v[72:75], off offset:64
	v_cvt_pk_bf16_f32 v238, v72, v73
	v_cvt_pk_bf16_f32 v239, v74, v75
	s_nop 0
	s_nop 1
	v_permlane32_swap_b32_e32 v236, v238
	v_permlane32_swap_b32_e32 v237, v239
	s_nop 1
	v_permlane16_swap_b32_e32 v236, v238
	v_permlane16_swap_b32_e32 v237, v239
	v_lshl_add_u64 v[242:243], v[92:93], 0, v[240:241]
	s_nop 0
	global_store_dwordx4 v[242:243], v[236:239], off sc1
	s_nop 1
	v_mov_b32_e32 v82, 0
	v_mov_b32_e32 v83, 0
	v_mov_b32_e32 v84, 0
	v_mov_b32_e32 v85, 0
	v_lshl_add_u64 v[92:93], v[90:91], 0, s[28:29]
	v_mul_f32_e32 v73, v73, v73
	v_mul_f32_e32 v75, v75, v75
	v_fmac_f32_e32 v73, v72, v72
	v_fmac_f32_e32 v75, v74, v74
	v_add_f32_e32 v72, v73, v75
	v_add_f32_e32 v72, v76, v72
	v_pk_add_f32 v[70:71], v[70:71], v[84:85]
	v_pk_add_f32 v[68:69], v[68:69], v[82:83]
	global_store_dwordx4 v[86:87], v[68:71], off offset:512
	v_cvt_pk_bf16_f32 v236, v68, v69
	v_cvt_pk_bf16_f32 v237, v70, v71
	s_nop 0
	v_mov_b32_e32 v82, 0
	v_mov_b32_e32 v83, 0
	v_mov_b32_e32 v84, 0
	v_mov_b32_e32 v85, 0
	v_mul_f32_e32 v69, v69, v69
	v_mul_f32_e32 v71, v71, v71
	v_fmac_f32_e32 v69, v68, v68
	v_fmac_f32_e32 v71, v70, v70
	v_add_f32_e32 v68, v69, v71
	v_add_f32_e32 v68, v72, v68
	v_pk_add_f32 v[66:67], v[66:67], v[84:85]
	v_pk_add_f32 v[64:65], v[64:65], v[82:83]
	v_mul_f32_e32 v70, v67, v67
	v_mul_f32_e32 v69, v65, v65
	v_fmac_f32_e32 v69, v64, v64
	v_fmac_f32_e32 v70, v66, v66
	v_add_f32_e32 v69, v69, v70
	v_add_f32_e32 v70, v68, v69
	ds_bpermute_b32 v71, v116, v70
	global_store_dwordx4 v[86:87], v[64:67], off offset:576
	v_cvt_pk_bf16_f32 v238, v64, v65
	v_cvt_pk_bf16_f32 v239, v66, v67
	s_waitcnt lgkmcnt(0)
	s_nop 0
	v_add_f32_e32 v64, v70, v71
	ds_bpermute_b32 v65, v114, v64
	v_lshl_add_u64 v[66:67], v[90:91], 0, s[30:31]
	s_nop 1
	v_permlane32_swap_b32_e32 v236, v238
	v_permlane32_swap_b32_e32 v237, v239
	s_nop 1
	v_permlane16_swap_b32_e32 v236, v238
	v_permlane16_swap_b32_e32 v237, v239
	v_lshl_add_u64 v[242:243], v[66:67], 0, v[240:241]
	s_nop 0
	global_store_dwordx4 v[242:243], v[236:239], off sc1
	s_nop 1
	s_and_saveexec_b64 s[44:45], s[4:5]
	s_cbranch_execz .LBB0_307
	s_waitcnt lgkmcnt(0)
	v_add_f32_e32 v66, v64, v65
	v_lshlrev_b64 v[64:65], 7, v[80:81]
	v_lshl_add_u64 v[64:65], s[2:3], 0, v[64:65]
	v_lshl_add_u64 v[64:65], s[42:43], 2, v[64:65]
	s_lshl_b32 s10, s55, 2
	v_lshl_add_u64 v[64:65], v[64:65], 0, s[10:11]
	global_store_dword v[64:65], v66, off sc1
; __device__ __forceinline__ unsigned cvt_pk_bf16(float lo, float hi) { unsigned r; asm volatile("v_cvt_pk_bf16_f32 %0, %1, %2" : "=v"(r) : "v"(lo), "v"(hi)); return r; }
; __device__ __forceinline__ void st_wt8(void* ptr, u32x2 v) { asm volatile("global_store_dwordx2 %0, %1, off sc1" :: "v"(ptr), "v"(v) : "memory"); }
; __device__ __forceinline__ void st_wt4(void* ptr, unsigned v) { asm volatile("global_store_dword %0, %1, off sc1" :: "v"(ptr), "v"(v) : "memory"); }
;     __device__ __forceinline__ void operator()(const f32x4 (&acc)[2][2][4][2], const pg8::Unit& u, int wr, int wc, int fr, int fq) const {
;     ...
;                 const int row = row0 + ai * 128 + m * 16;
;                 float* orow = oy + (size_t)row * DM + col0;
;                 const float* xr = FIRST ? ((row < MP ? xp + (size_t)row * DM : xs + (size_t)(row - MP) * DM) + col0) : orow;
;                 float q = 0.f;
; #pragma unroll
;                 for (int bj = 0; bj < 2; ++bj)
; #pragma unroll
;                     for (int n = 0; n < 2; ++n) {
;                         const f32x4 xv = *(const f32x4*)(xr + bj * 128 + n * 16);
;                         const f32x4 o = xv + acc[ai][bj][m][n];
;                         *(f32x4*)(orow + bj * 128 + n * 16) = o;
;                         q += (o[0] * o[0] + o[1] * o[1]) + (o[2] * o[2] + o[3] * o[3]);
;                         if (FIRST) { u32x2 w; w.x = cvt_pk_bf16(o[0], o[1]); w.y = cvt_pk_bf16(o[2], o[3]); st_wt8(xb + (size_t)row * DM + col0 + bj * 128 + n * 16, w); }
;                     }
;                 q += __shfl_xor(q, 16); q += __shfl_xor(q, 32);
;                 if (fq == 0) { if (FIRST) st_wt4(ss + (size_t)row * 32 + u.pn * 4 + wc, __float_as_uint(q)); else ss[(size_t)row * 32 + u.pn * 4 + wc] = q; }
.LBB0_307:
	s_or_b64 exec, exec, s[44:45]
	v_add_u32_e32 v64, 0x80, v144
	s_waitcnt lgkmcnt(0)
	v_ashrrev_i32_e32 v65, 31, v64
	v_readlane_b32 s68, v234, 3
	v_add_u32_e32 v132, 0xffffe080, v144
	v_lshlrev_b64 v[70:71], 13, v[64:65]
	v_readlane_b32 s69, v234, 4
	v_readlane_b32 s70, v234, 5
	v_readlane_b32 s71, v234, 6
	v_lshlrev_b64 v[68:69], 13, v[132:133]
	s_movk_i32 s9, 0x1f80
	v_lshl_add_u64 v[66:67], s[68:69], 0, v[70:71]
	v_lshl_add_u64 v[68:69], s[70:71], 0, v[68:69]
	v_cmp_gt_i32_e32 vcc, s9, v144
	v_lshlrev_b64 v[74:75], 12, v[64:65]
	v_lshl_add_u64 v[70:71], s[84:85], 0, v[70:71]
	v_cndmask_b32_e32 v67, v69, v67, vcc
	v_cndmask_b32_e32 v66, v68, v66, vcc
	v_lshl_add_u64 v[72:73], v[66:67], 0, v[142:143]
	v_mov_b32_e32 v66, 0
	v_mov_b32_e32 v67, 0
	v_mov_b32_e32 v68, 0
	v_mov_b32_e32 v69, 0
	v_lshl_add_u64 v[74:75], s[20:21], 0, v[74:75]
	v_lshl_add_u64 v[70:71], v[70:71], 0, v[142:143]
	v_lshl_add_u64 v[74:75], v[140:141], 1, v[74:75]
	v_lshl_add_u64 v[76:77], v[74:75], 0, 32
	v_readlane_b32 s72, v234, 7
	v_readlane_b32 s73, v234, 8
	v_readlane_b32 s74, v234, 9
	v_readlane_b32 s75, v234, 10
	v_readlane_b32 s76, v234, 11
	v_readlane_b32 s77, v234, 12
	v_readlane_b32 s78, v234, 13
	v_readlane_b32 s79, v234, 14
	v_readlane_b32 s80, v234, 15
	v_readlane_b32 s81, v234, 16
	v_readlane_b32 s82, v234, 17
	v_readlane_b32 s83, v234, 18
	v_pk_add_f32 v[62:63], v[62:63], v[68:69]
	v_pk_add_f32 v[60:61], v[60:61], v[66:67]
	global_store_dwordx4 v[70:71], v[60:63], off
	v_cvt_pk_bf16_f32 v236, v60, v61
	v_cvt_pk_bf16_f32 v237, v62, v63
	s_nop 0
	v_mov_b32_e32 v66, 0
	v_mov_b32_e32 v67, 0
	v_mov_b32_e32 v68, 0
	v_mov_b32_e32 v69, 0
	v_mul_f32_e32 v61, v61, v61
	v_mul_f32_e32 v63, v63, v63
	v_fmac_f32_e32 v61, v60, v60
	v_fmac_f32_e32 v63, v62, v62
	v_add_f32_e32 v60, v61, v63
	v_pk_add_f32 v[58:59], v[58:59], v[68:69]
	v_pk_add_f32 v[56:57], v[56:57], v[66:67]
	global_store_dwordx4 v[70:71], v[56:59], off offset:64
	v_cvt_pk_bf16_f32 v238, v56, v57
	v_cvt_pk_bf16_f32 v239, v58, v59
	s_nop 0
	s_nop 1
	v_permlane32_swap_b32_e32 v236, v238
	v_permlane32_swap_b32_e32 v237, v239
	s_nop 1
	v_permlane16_swap_b32_e32 v236, v238
	v_permlane16_swap_b32_e32 v237, v239
	v_lshl_add_u64 v[242:243], v[76:77], 0, v[240:241]
	s_nop 0
	global_store_dwordx4 v[242:243], v[236:239], off sc1
	s_nop 1
	v_mov_b32_e32 v66, 0
	v_mov_b32_e32 v67, 0
	v_mov_b32_e32 v68, 0
	v_mov_b32_e32 v69, 0
	v_lshl_add_u64 v[76:77], v[74:75], 0, s[28:29]
	v_mul_f32_e32 v57, v57, v57
	v_mul_f32_e32 v59, v59, v59
	v_fmac_f32_e32 v57, v56, v56
	v_fmac_f32_e32 v59, v58, v58
	v_add_f32_e32 v56, v57, v59
	v_add_f32_e32 v56, v60, v56
	v_pk_add_f32 v[54:55], v[54:55], v[68:69]
	v_pk_add_f32 v[52:53], v[52:53], v[66:67]
	global_store_dwordx4 v[70:71], v[52:55], off offset:512
	v_cvt_pk_bf16_f32 v236, v52, v53
	v_cvt_pk_bf16_f32 v237, v54, v55
	s_nop 0
	v_mov_b32_e32 v66, 0
	v_mov_b32_e32 v67, 0
	v_mov_b32_e32 v68, 0
	v_mov_b32_e32 v69, 0
	v_mul_f32_e32 v53, v53, v53
	v_mul_f32_e32 v55, v55, v55
	v_fmac_f32_e32 v53, v52, v52
	v_fmac_f32_e32 v55, v54, v54
	v_add_f32_e32 v52, v53, v55
	v_add_f32_e32 v52, v56, v52
	v_pk_add_f32 v[50:51], v[50:51], v[68:69]
	v_pk_add_f32 v[48:49], v[48:49], v[66:67]
	v_mul_f32_e32 v54, v51, v51
	v_mul_f32_e32 v53, v49, v49
	v_fmac_f32_e32 v53, v48, v48
	v_fmac_f32_e32 v54, v50, v50
	v_add_f32_e32 v53, v53, v54
	v_add_f32_e32 v54, v52, v53
	ds_bpermute_b32 v55, v116, v54
	global_store_dwordx4 v[70:71], v[48:51], off offset:576
	v_cvt_pk_bf16_f32 v238, v48, v49
	v_cvt_pk_bf16_f32 v239, v50, v51
	s_waitcnt lgkmcnt(0)
	s_nop 0
	v_add_f32_e32 v48, v54, v55
	ds_bpermute_b32 v49, v114, v48
	v_lshl_add_u64 v[50:51], v[74:75], 0, s[30:31]
	s_nop 1
	v_permlane32_swap_b32_e32 v236, v238
	v_permlane32_swap_b32_e32 v237, v239
	s_nop 1
	v_permlane16_swap_b32_e32 v236, v238
	v_permlane16_swap_b32_e32 v237, v239
	v_lshl_add_u64 v[242:243], v[50:51], 0, v[240:241]
	s_nop 0
	global_store_dwordx4 v[242:243], v[236:239], off sc1
	s_nop 1
	s_and_saveexec_b64 s[44:45], s[4:5]
	s_cbranch_execz .LBB0_309
	s_waitcnt lgkmcnt(0)
	v_add_f32_e32 v50, v48, v49
	v_lshlrev_b64 v[48:49], 7, v[64:65]
	v_lshl_add_u64 v[48:49], s[2:3], 0, v[48:49]
	v_lshl_add_u64 v[48:49], s[42:43], 2, v[48:49]
	s_lshl_b32 s10, s55, 2
	v_lshl_add_u64 v[48:49], v[48:49], 0, s[10:11]
	global_store_dword v[48:49], v50, off sc1
; __device__ __forceinline__ unsigned cvt_pk_bf16(float lo, float hi) { unsigned r; asm volatile("v_cvt_pk_bf16_f32 %0, %1, %2" : "=v"(r) : "v"(lo), "v"(hi)); return r; }
; __device__ __forceinline__ void st_wt8(void* ptr, u32x2 v) { asm volatile("global_store_dwordx2 %0, %1, off sc1" :: "v"(ptr), "v"(v) : "memory"); }
; __device__ __forceinline__ void st_wt4(void* ptr, unsigned v) { asm volatile("global_store_dword %0, %1, off sc1" :: "v"(ptr), "v"(v) : "memory"); }
;     __device__ __forceinline__ void operator()(const f32x4 (&acc)[2][2][4][2], const pg8::Unit& u, int wr, int wc, int fr, int fq) const {
;     ...
;                 const int row = row0 + ai * 128 + m * 16;
;                 float* orow = oy + (size_t)row * DM + col0;
;                 const float* xr = FIRST ? ((row < MP ? xp + (size_t)row * DM : xs + (size_t)(row - MP) * DM) + col0) : orow;
;                 float q = 0.f;
; #pragma unroll
;                 for (int bj = 0; bj < 2; ++bj)
; #pragma unroll
;                     for (int n = 0; n < 2; ++n) {
;                         const f32x4 xv = *(const f32x4*)(xr + bj * 128 + n * 16);
;                         const f32x4 o = xv + acc[ai][bj][m][n];
;                         *(f32x4*)(orow + bj * 128 + n * 16) = o;
;                         q += (o[0] * o[0] + o[1] * o[1]) + (o[2] * o[2] + o[3] * o[3]);
;                         if (FIRST) { u32x2 w; w.x = cvt_pk_bf16(o[0], o[1]); w.y = cvt_pk_bf16(o[2], o[3]); st_wt8(xb + (size_t)row * DM + col0 + bj * 128 + n * 16, w); }
;                     }
;                 q += __shfl_xor(q, 16); q += __shfl_xor(q, 32);
;                 if (fq == 0) { if (FIRST) st_wt4(ss + (size_t)row * 32 + u.pn * 4 + wc, __float_as_uint(q)); else ss[(size_t)row * 32 + u.pn * 4 + wc] = q; }
.LBB0_309:
	s_or_b64 exec, exec, s[44:45]
	v_add_u32_e32 v48, 0x90, v144
	s_waitcnt lgkmcnt(0)
	v_ashrrev_i32_e32 v49, 31, v48
	v_readlane_b32 s68, v234, 3
	v_add_u32_e32 v132, 0xffffe090, v144
	v_lshlrev_b64 v[54:55], 13, v[48:49]
	v_readlane_b32 s69, v234, 4
	v_readlane_b32 s70, v234, 5
	v_readlane_b32 s71, v234, 6
	v_lshlrev_b64 v[52:53], 13, v[132:133]
	s_movk_i32 s9, 0x1f70
	v_lshl_add_u64 v[50:51], s[68:69], 0, v[54:55]
	v_lshl_add_u64 v[52:53], s[70:71], 0, v[52:53]
	v_cmp_gt_i32_e32 vcc, s9, v144
	v_lshlrev_b64 v[58:59], 12, v[48:49]
	v_lshl_add_u64 v[54:55], s[84:85], 0, v[54:55]
	v_cndmask_b32_e32 v51, v53, v51, vcc
	v_cndmask_b32_e32 v50, v52, v50, vcc
	v_lshl_add_u64 v[56:57], v[50:51], 0, v[142:143]
	v_mov_b32_e32 v50, 0
	v_mov_b32_e32 v51, 0
	v_mov_b32_e32 v52, 0
	v_mov_b32_e32 v53, 0
	v_lshl_add_u64 v[58:59], s[20:21], 0, v[58:59]
	v_lshl_add_u64 v[54:55], v[54:55], 0, v[142:143]
	v_lshl_add_u64 v[58:59], v[140:141], 1, v[58:59]
	v_lshl_add_u64 v[60:61], v[58:59], 0, 32
	v_readlane_b32 s72, v234, 7
	v_readlane_b32 s73, v234, 8
	v_readlane_b32 s74, v234, 9
	v_readlane_b32 s75, v234, 10
	v_readlane_b32 s76, v234, 11
	v_readlane_b32 s77, v234, 12
	v_readlane_b32 s78, v234, 13
	v_readlane_b32 s79, v234, 14
	v_readlane_b32 s80, v234, 15
	v_readlane_b32 s81, v234, 16
	v_readlane_b32 s82, v234, 17
	v_readlane_b32 s83, v234, 18
	v_pk_add_f32 v[46:47], v[46:47], v[52:53]
	v_pk_add_f32 v[44:45], v[44:45], v[50:51]
	global_store_dwordx4 v[54:55], v[44:47], off
	v_cvt_pk_bf16_f32 v236, v44, v45
	v_cvt_pk_bf16_f32 v237, v46, v47
	s_nop 0
	v_mov_b32_e32 v50, 0
	v_mov_b32_e32 v51, 0
	v_mov_b32_e32 v52, 0
	v_mov_b32_e32 v53, 0
	v_mul_f32_e32 v45, v45, v45
	v_mul_f32_e32 v47, v47, v47
	v_fmac_f32_e32 v45, v44, v44
	v_fmac_f32_e32 v47, v46, v46
	v_add_f32_e32 v44, v45, v47
	v_pk_add_f32 v[42:43], v[42:43], v[52:53]
	v_pk_add_f32 v[40:41], v[40:41], v[50:51]
	global_store_dwordx4 v[54:55], v[40:43], off offset:64
	v_cvt_pk_bf16_f32 v238, v40, v41
	v_cvt_pk_bf16_f32 v239, v42, v43
	s_nop 0
	s_nop 1
	v_permlane32_swap_b32_e32 v236, v238
	v_permlane32_swap_b32_e32 v237, v239
	s_nop 1
	v_permlane16_swap_b32_e32 v236, v238
	v_permlane16_swap_b32_e32 v237, v239
	v_lshl_add_u64 v[242:243], v[60:61], 0, v[240:241]
	s_nop 0
	global_store_dwordx4 v[242:243], v[236:239], off sc1
	s_nop 1
	v_mov_b32_e32 v50, 0
	v_mov_b32_e32 v51, 0
	v_mov_b32_e32 v52, 0
	v_mov_b32_e32 v53, 0
	v_lshl_add_u64 v[60:61], v[58:59], 0, s[28:29]
	v_mul_f32_e32 v41, v41, v41
	v_mul_f32_e32 v43, v43, v43
	v_fmac_f32_e32 v41, v40, v40
	v_fmac_f32_e32 v43, v42, v42
	v_add_f32_e32 v40, v41, v43
	v_add_f32_e32 v40, v44, v40
	v_pk_add_f32 v[38:39], v[38:39], v[52:53]
	v_pk_add_f32 v[36:37], v[36:37], v[50:51]
	global_store_dwordx4 v[54:55], v[36:39], off offset:512
	v_cvt_pk_bf16_f32 v236, v36, v37
	v_cvt_pk_bf16_f32 v237, v38, v39
	s_nop 0
	v_mov_b32_e32 v50, 0
	v_mov_b32_e32 v51, 0
	v_mov_b32_e32 v52, 0
	v_mov_b32_e32 v53, 0
	v_mul_f32_e32 v37, v37, v37
	v_mul_f32_e32 v39, v39, v39
	v_fmac_f32_e32 v37, v36, v36
	v_fmac_f32_e32 v39, v38, v38
	v_add_f32_e32 v36, v37, v39
	v_add_f32_e32 v36, v40, v36
	v_pk_add_f32 v[34:35], v[34:35], v[52:53]
	v_pk_add_f32 v[32:33], v[32:33], v[50:51]
	v_mul_f32_e32 v38, v35, v35
	v_mul_f32_e32 v37, v33, v33
	v_fmac_f32_e32 v37, v32, v32
	v_fmac_f32_e32 v38, v34, v34
	v_add_f32_e32 v37, v37, v38
	v_add_f32_e32 v38, v36, v37
	ds_bpermute_b32 v39, v116, v38
	global_store_dwordx4 v[54:55], v[32:35], off offset:576
	v_cvt_pk_bf16_f32 v238, v32, v33
	v_cvt_pk_bf16_f32 v239, v34, v35
	s_waitcnt lgkmcnt(0)
	s_nop 0
	v_add_f32_e32 v32, v38, v39
	ds_bpermute_b32 v33, v114, v32
	v_lshl_add_u64 v[34:35], v[58:59], 0, s[30:31]
	s_nop 1
	v_permlane32_swap_b32_e32 v236, v238
	v_permlane32_swap_b32_e32 v237, v239
	s_nop 1
	v_permlane16_swap_b32_e32 v236, v238
	v_permlane16_swap_b32_e32 v237, v239
	v_lshl_add_u64 v[242:243], v[34:35], 0, v[240:241]
	s_nop 0
	global_store_dwordx4 v[242:243], v[236:239], off sc1
	s_nop 1
	s_and_saveexec_b64 s[44:45], s[4:5]
	s_cbranch_execz .LBB0_311
	s_waitcnt lgkmcnt(0)
	v_add_f32_e32 v34, v32, v33
	v_lshlrev_b64 v[32:33], 7, v[48:49]
	v_lshl_add_u64 v[32:33], s[2:3], 0, v[32:33]
	v_lshl_add_u64 v[32:33], s[42:43], 2, v[32:33]
	s_lshl_b32 s10, s55, 2
	v_lshl_add_u64 v[32:33], v[32:33], 0, s[10:11]
	global_store_dword v[32:33], v34, off sc1
; __device__ __forceinline__ unsigned cvt_pk_bf16(float lo, float hi) { unsigned r; asm volatile("v_cvt_pk_bf16_f32 %0, %1, %2" : "=v"(r) : "v"(lo), "v"(hi)); return r; }
; __device__ __forceinline__ void st_wt8(void* ptr, u32x2 v) { asm volatile("global_store_dwordx2 %0, %1, off sc1" :: "v"(ptr), "v"(v) : "memory"); }
; __device__ __forceinline__ void st_wt4(void* ptr, unsigned v) { asm volatile("global_store_dword %0, %1, off sc1" :: "v"(ptr), "v"(v) : "memory"); }
;     __device__ __forceinline__ void operator()(const f32x4 (&acc)[2][2][4][2], const pg8::Unit& u, int wr, int wc, int fr, int fq) const {
;     ...
;                 const int row = row0 + ai * 128 + m * 16;
;                 float* orow = oy + (size_t)row * DM + col0;
;                 const float* xr = FIRST ? ((row < MP ? xp + (size_t)row * DM : xs + (size_t)(row - MP) * DM) + col0) : orow;
;                 float q = 0.f;
; #pragma unroll
;                 for (int bj = 0; bj < 2; ++bj)
; #pragma unroll
;                     for (int n = 0; n < 2; ++n) {
;                         const f32x4 xv = *(const f32x4*)(xr + bj * 128 + n * 16);
;                         const f32x4 o = xv + acc[ai][bj][m][n];
;                         *(f32x4*)(orow + bj * 128 + n * 16) = o;
;                         q += (o[0] * o[0] + o[1] * o[1]) + (o[2] * o[2] + o[3] * o[3]);
;                         if (FIRST) { u32x2 w; w.x = cvt_pk_bf16(o[0], o[1]); w.y = cvt_pk_bf16(o[2], o[3]); st_wt8(xb + (size_t)row * DM + col0 + bj * 128 + n * 16, w); }
;                     }
;                 q += __shfl_xor(q, 16); q += __shfl_xor(q, 32);
;                 if (fq == 0) { if (FIRST) st_wt4(ss + (size_t)row * 32 + u.pn * 4 + wc, __float_as_uint(q)); else ss[(size_t)row * 32 + u.pn * 4 + wc] = q; }
.LBB0_311:
	s_or_b64 exec, exec, s[44:45]
	v_add_u32_e32 v32, 0xa0, v144
	s_waitcnt lgkmcnt(0)
	v_ashrrev_i32_e32 v33, 31, v32
	v_readlane_b32 s68, v234, 3
	v_add_u32_e32 v132, 0xffffe0a0, v144
	v_lshlrev_b64 v[38:39], 13, v[32:33]
	v_readlane_b32 s69, v234, 4
	v_readlane_b32 s70, v234, 5
	v_readlane_b32 s71, v234, 6
	v_lshlrev_b64 v[36:37], 13, v[132:133]
	s_movk_i32 s9, 0x1f60
	v_lshl_add_u64 v[34:35], s[68:69], 0, v[38:39]
	v_lshl_add_u64 v[36:37], s[70:71], 0, v[36:37]
	v_cmp_gt_i32_e32 vcc, s9, v144
	v_lshlrev_b64 v[42:43], 12, v[32:33]
	v_lshl_add_u64 v[38:39], s[84:85], 0, v[38:39]
	v_cndmask_b32_e32 v35, v37, v35, vcc
	v_cndmask_b32_e32 v34, v36, v34, vcc
	v_lshl_add_u64 v[40:41], v[34:35], 0, v[142:143]
	v_mov_b32_e32 v34, 0
	v_mov_b32_e32 v35, 0
	v_mov_b32_e32 v36, 0
	v_mov_b32_e32 v37, 0
	v_lshl_add_u64 v[42:43], s[20:21], 0, v[42:43]
	v_lshl_add_u64 v[38:39], v[38:39], 0, v[142:143]
	v_lshl_add_u64 v[42:43], v[140:141], 1, v[42:43]
	v_lshl_add_u64 v[44:45], v[42:43], 0, 32
	v_readlane_b32 s72, v234, 7
	v_readlane_b32 s73, v234, 8
	v_readlane_b32 s74, v234, 9
	v_readlane_b32 s75, v234, 10
	v_readlane_b32 s76, v234, 11
	v_readlane_b32 s77, v234, 12
	v_readlane_b32 s78, v234, 13
	v_readlane_b32 s79, v234, 14
	v_readlane_b32 s80, v234, 15
	v_readlane_b32 s81, v234, 16
	v_readlane_b32 s82, v234, 17
	v_readlane_b32 s83, v234, 18
	v_pk_add_f32 v[30:31], v[30:31], v[36:37]
	v_pk_add_f32 v[28:29], v[28:29], v[34:35]
	global_store_dwordx4 v[38:39], v[28:31], off
	v_cvt_pk_bf16_f32 v236, v28, v29
	v_cvt_pk_bf16_f32 v237, v30, v31
	s_nop 0
	v_mov_b32_e32 v34, 0
	v_mov_b32_e32 v35, 0
	v_mov_b32_e32 v36, 0
	v_mov_b32_e32 v37, 0
	v_mul_f32_e32 v29, v29, v29
	v_mul_f32_e32 v31, v31, v31
	v_fmac_f32_e32 v29, v28, v28
	v_fmac_f32_e32 v31, v30, v30
	v_add_f32_e32 v28, v29, v31
	v_pk_add_f32 v[26:27], v[26:27], v[36:37]
	v_pk_add_f32 v[24:25], v[24:25], v[34:35]
	global_store_dwordx4 v[38:39], v[24:27], off offset:64
	v_cvt_pk_bf16_f32 v238, v24, v25
	v_cvt_pk_bf16_f32 v239, v26, v27
	s_nop 0
	s_nop 1
	v_permlane32_swap_b32_e32 v236, v238
	v_permlane32_swap_b32_e32 v237, v239
	s_nop 1
	v_permlane16_swap_b32_e32 v236, v238
	v_permlane16_swap_b32_e32 v237, v239
	v_lshl_add_u64 v[242:243], v[44:45], 0, v[240:241]
	s_nop 0
	global_store_dwordx4 v[242:243], v[236:239], off sc1
	s_nop 1
	v_mov_b32_e32 v34, 0
	v_mov_b32_e32 v35, 0
	v_mov_b32_e32 v36, 0
	v_mov_b32_e32 v37, 0
	v_lshl_add_u64 v[44:45], v[42:43], 0, s[28:29]
	v_mul_f32_e32 v25, v25, v25
	v_mul_f32_e32 v27, v27, v27
	v_fmac_f32_e32 v25, v24, v24
	v_fmac_f32_e32 v27, v26, v26
	v_add_f32_e32 v24, v25, v27
	v_add_f32_e32 v24, v28, v24
	v_pk_add_f32 v[22:23], v[22:23], v[36:37]
	v_pk_add_f32 v[20:21], v[20:21], v[34:35]
	global_store_dwordx4 v[38:39], v[20:23], off offset:512
	v_cvt_pk_bf16_f32 v236, v20, v21
	v_cvt_pk_bf16_f32 v237, v22, v23
	s_nop 0
	v_mov_b32_e32 v34, 0
	v_mov_b32_e32 v35, 0
	v_mov_b32_e32 v36, 0
	v_mov_b32_e32 v37, 0
	v_mul_f32_e32 v21, v21, v21
	v_mul_f32_e32 v23, v23, v23
	v_fmac_f32_e32 v21, v20, v20
	v_fmac_f32_e32 v23, v22, v22
	v_add_f32_e32 v20, v21, v23
	v_add_f32_e32 v20, v24, v20
	v_pk_add_f32 v[18:19], v[18:19], v[36:37]
	v_pk_add_f32 v[16:17], v[16:17], v[34:35]
	v_mul_f32_e32 v22, v19, v19
	v_mul_f32_e32 v21, v17, v17
	v_fmac_f32_e32 v21, v16, v16
	v_fmac_f32_e32 v22, v18, v18
	v_add_f32_e32 v21, v21, v22
	v_add_f32_e32 v22, v20, v21
	ds_bpermute_b32 v23, v116, v22
	global_store_dwordx4 v[38:39], v[16:19], off offset:576
	v_cvt_pk_bf16_f32 v238, v16, v17
	v_cvt_pk_bf16_f32 v239, v18, v19
	s_waitcnt lgkmcnt(0)
	s_nop 0
	v_add_f32_e32 v16, v22, v23
	ds_bpermute_b32 v17, v114, v16
	v_lshl_add_u64 v[18:19], v[42:43], 0, s[30:31]
	s_nop 1
	v_permlane32_swap_b32_e32 v236, v238
	v_permlane32_swap_b32_e32 v237, v239
	s_nop 1
	v_permlane16_swap_b32_e32 v236, v238
	v_permlane16_swap_b32_e32 v237, v239
	v_lshl_add_u64 v[242:243], v[18:19], 0, v[240:241]
	s_nop 0
	global_store_dwordx4 v[242:243], v[236:239], off sc1
	s_nop 1
	s_and_saveexec_b64 s[44:45], s[4:5]
	s_cbranch_execz .LBB0_313
	s_waitcnt lgkmcnt(0)
	v_add_f32_e32 v18, v16, v17
	v_lshlrev_b64 v[16:17], 7, v[32:33]
	v_lshl_add_u64 v[16:17], s[2:3], 0, v[16:17]
	v_lshl_add_u64 v[16:17], s[42:43], 2, v[16:17]
	s_lshl_b32 s10, s55, 2
	v_lshl_add_u64 v[16:17], v[16:17], 0, s[10:11]
	global_store_dword v[16:17], v18, off sc1
; __device__ __forceinline__ unsigned cvt_pk_bf16(float lo, float hi) { unsigned r; asm volatile("v_cvt_pk_bf16_f32 %0, %1, %2" : "=v"(r) : "v"(lo), "v"(hi)); return r; }
; __device__ __forceinline__ void st_wt8(void* ptr, u32x2 v) { asm volatile("global_store_dwordx2 %0, %1, off sc1" :: "v"(ptr), "v"(v) : "memory"); }
; __device__ __forceinline__ void st_wt4(void* ptr, unsigned v) { asm volatile("global_store_dword %0, %1, off sc1" :: "v"(ptr), "v"(v) : "memory"); }
;     __device__ __forceinline__ void operator()(const f32x4 (&acc)[2][2][4][2], const pg8::Unit& u, int wr, int wc, int fr, int fq) const {
;     ...
;                 const int row = row0 + ai * 128 + m * 16;
;                 float* orow = oy + (size_t)row * DM + col0;
;                 const float* xr = FIRST ? ((row < MP ? xp + (size_t)row * DM : xs + (size_t)(row - MP) * DM) + col0) : orow;
;                 float q = 0.f;
; #pragma unroll
;                 for (int bj = 0; bj < 2; ++bj)
; #pragma unroll
;                     for (int n = 0; n < 2; ++n) {
;                         const f32x4 xv = *(const f32x4*)(xr + bj * 128 + n * 16);
;                         const f32x4 o = xv + acc[ai][bj][m][n];
;                         *(f32x4*)(orow + bj * 128 + n * 16) = o;
;                         q += (o[0] * o[0] + o[1] * o[1]) + (o[2] * o[2] + o[3] * o[3]);
;                         if (FIRST) { u32x2 w; w.x = cvt_pk_bf16(o[0], o[1]); w.y = cvt_pk_bf16(o[2], o[3]); st_wt8(xb + (size_t)row * DM + col0 + bj * 128 + n * 16, w); }
;                     }
;                 q += __shfl_xor(q, 16); q += __shfl_xor(q, 32);
;                 if (fq == 0) { if (FIRST) st_wt4(ss + (size_t)row * 32 + u.pn * 4 + wc, __float_as_uint(q)); else ss[(size_t)row * 32 + u.pn * 4 + wc] = q; }
;             }
.LBB0_313:
	s_or_b64 exec, exec, s[44:45]
	v_add_u32_e32 v16, 0xb0, v144
	s_waitcnt lgkmcnt(0)
	v_ashrrev_i32_e32 v17, 31, v16
	v_readlane_b32 s68, v234, 3
	v_add_u32_e32 v132, 0xffffe0b0, v144
	v_lshlrev_b64 v[22:23], 13, v[16:17]
	v_readlane_b32 s69, v234, 4
	v_readlane_b32 s70, v234, 5
	v_readlane_b32 s71, v234, 6
	v_lshlrev_b64 v[20:21], 13, v[132:133]
	s_movk_i32 s9, 0x1f50
	v_lshl_add_u64 v[18:19], s[68:69], 0, v[22:23]
	v_lshl_add_u64 v[20:21], s[70:71], 0, v[20:21]
	v_cmp_gt_i32_e32 vcc, s9, v144
	v_lshlrev_b64 v[26:27], 12, v[16:17]
	v_lshl_add_u64 v[22:23], s[84:85], 0, v[22:23]
	v_cndmask_b32_e32 v19, v21, v19, vcc
	v_cndmask_b32_e32 v18, v20, v18, vcc
	v_lshl_add_u64 v[24:25], v[18:19], 0, v[142:143]
	v_mov_b32_e32 v18, 0
	v_mov_b32_e32 v19, 0
	v_mov_b32_e32 v20, 0
	v_mov_b32_e32 v21, 0
	v_lshl_add_u64 v[26:27], s[20:21], 0, v[26:27]
	v_lshl_add_u64 v[22:23], v[22:23], 0, v[142:143]
	v_lshl_add_u64 v[26:27], v[140:141], 1, v[26:27]
	v_lshl_add_u64 v[28:29], v[26:27], 0, 32
	v_readlane_b32 s72, v234, 7
	v_readlane_b32 s73, v234, 8
	v_readlane_b32 s74, v234, 9
	v_readlane_b32 s75, v234, 10
	v_readlane_b32 s76, v234, 11
	v_readlane_b32 s77, v234, 12
	v_readlane_b32 s78, v234, 13
	v_readlane_b32 s79, v234, 14
	v_readlane_b32 s80, v234, 15
	v_readlane_b32 s81, v234, 16
	v_readlane_b32 s82, v234, 17
	v_readlane_b32 s83, v234, 18
	v_pk_add_f32 v[14:15], v[14:15], v[20:21]
	v_pk_add_f32 v[12:13], v[12:13], v[18:19]
	global_store_dwordx4 v[22:23], v[12:15], off
	v_cvt_pk_bf16_f32 v236, v12, v13
	v_cvt_pk_bf16_f32 v237, v14, v15
	s_nop 0
	v_mov_b32_e32 v18, 0
	v_mov_b32_e32 v19, 0
	v_mov_b32_e32 v20, 0
	v_mov_b32_e32 v21, 0
	v_mul_f32_e32 v13, v13, v13
	v_mul_f32_e32 v15, v15, v15
	v_fmac_f32_e32 v13, v12, v12
	v_fmac_f32_e32 v15, v14, v14
	v_add_f32_e32 v12, v13, v15
	v_pk_add_f32 v[10:11], v[10:11], v[20:21]
	v_pk_add_f32 v[8:9], v[8:9], v[18:19]
	global_store_dwordx4 v[22:23], v[8:11], off offset:64
	v_cvt_pk_bf16_f32 v238, v8, v9
	v_cvt_pk_bf16_f32 v239, v10, v11
	s_nop 0
	s_nop 1
	v_permlane32_swap_b32_e32 v236, v238
	v_permlane32_swap_b32_e32 v237, v239
	s_nop 1
	v_permlane16_swap_b32_e32 v236, v238
	v_permlane16_swap_b32_e32 v237, v239
	v_lshl_add_u64 v[242:243], v[28:29], 0, v[240:241]
	s_nop 0
	global_store_dwordx4 v[242:243], v[236:239], off sc1
	s_nop 1
	v_mov_b32_e32 v18, 0
	v_mov_b32_e32 v19, 0
	v_mov_b32_e32 v20, 0
	v_mov_b32_e32 v21, 0
	v_lshl_add_u64 v[28:29], v[26:27], 0, s[28:29]
	v_mul_f32_e32 v9, v9, v9
	v_mul_f32_e32 v11, v11, v11
	v_fmac_f32_e32 v9, v8, v8
	v_fmac_f32_e32 v11, v10, v10
	v_add_f32_e32 v8, v9, v11
	v_add_f32_e32 v8, v12, v8
	v_pk_add_f32 v[6:7], v[6:7], v[20:21]
	v_pk_add_f32 v[4:5], v[4:5], v[18:19]
	global_store_dwordx4 v[22:23], v[4:7], off offset:512
	v_cvt_pk_bf16_f32 v236, v4, v5
	v_cvt_pk_bf16_f32 v237, v6, v7
	s_nop 0
	v_mov_b32_e32 v18, 0
	v_mov_b32_e32 v19, 0
	v_mov_b32_e32 v20, 0
	v_mov_b32_e32 v21, 0
	v_mul_f32_e32 v5, v5, v5
	v_mul_f32_e32 v7, v7, v7
	v_fmac_f32_e32 v5, v4, v4
	v_fmac_f32_e32 v7, v6, v6
	v_add_f32_e32 v4, v5, v7
	v_add_f32_e32 v4, v8, v4
	v_pk_add_f32 v[2:3], v[2:3], v[20:21]
	v_pk_add_f32 v[0:1], v[0:1], v[18:19]
	v_mul_f32_e32 v6, v3, v3
	v_mul_f32_e32 v5, v1, v1
	v_fmac_f32_e32 v5, v0, v0
	v_fmac_f32_e32 v6, v2, v2
	v_add_f32_e32 v5, v5, v6
	v_add_f32_e32 v6, v4, v5
	ds_bpermute_b32 v7, v116, v6
	global_store_dwordx4 v[22:23], v[0:3], off offset:576
	v_cvt_pk_bf16_f32 v238, v0, v1
	v_cvt_pk_bf16_f32 v239, v2, v3
	s_waitcnt lgkmcnt(0)
	s_nop 0
	v_add_f32_e32 v0, v6, v7
	ds_bpermute_b32 v1, v114, v0
	v_lshl_add_u64 v[2:3], v[26:27], 0, s[30:31]
	s_nop 1
	v_permlane32_swap_b32_e32 v236, v238
	v_permlane32_swap_b32_e32 v237, v239
	s_nop 1
	v_permlane16_swap_b32_e32 v236, v238
	v_permlane16_swap_b32_e32 v237, v239
	v_lshl_add_u64 v[242:243], v[2:3], 0, v[240:241]
	s_nop 0
	global_store_dwordx4 v[242:243], v[236:239], off sc1
	s_nop 1
	s_and_saveexec_b64 s[44:45], s[4:5]
	s_cbranch_execnz .LBB0_316
	s_or_b64 exec, exec, s[44:45]
	s_andn2_b64 vcc, exec, s[36:37]
	s_mov_b64 s[36:37], -1
	s_cbranch_vccz .LBB0_317
